# v19 plus no-repeat MFMA order (consecutive MFMAs share neither A nor B fragment register), 44 K-loop blocks
# speedup vs baseline: 1.0213x; 1.0107x over previous
; #define PG8_STAGE(bufoff, gbase, voff) do { _Pragma("unroll") for (int _i = 0; _i < 2; ++_i) \
;         __builtin_amdgcn_global_load_lds((const unsigned*)((const char*)(gbase) + (voff)[_i]), (PG8_LAS unsigned*)(lds + (bufoff) + ldsw + _i * 8192), 16, 0, 0); } while (0)
; #define PG8_LDA(dst, b, h) do { _Pragma("unroll") for (int m = 0; m < 4; ++m) _Pragma("unroll") for (int k = 0; k < 2; ++k) dst[m][k] = *(const PG8_LAS bf16x8*)(lds + PG8_SA(b, h) + aoff + m * 2048 + k * 1024); } while (0)
; #define PG8_MMA(ai, bj, At, Bt) do { __builtin_amdgcn_s_setprio(1); _Pragma("unroll") for (int m = 0; m < 4; ++m) _Pragma("unroll") for (int n = 0; n < 2; ++n) _Pragma("unroll") for (int k = 0; k < 2; ++k) \
;         acc[ai][bj][m][n] = __builtin_amdgcn_mfma_f32_16x16x32_bf16(Bt[n][k], At[m][k], acc[ai][bj][m][n], 0, 0, 0); __builtin_amdgcn_s_setprio(0); } while (0)
; #define PG8_WAIT_V(n) asm volatile("s_waitcnt vmcnt(" #n ")" ::: "memory")
; #define PG8_WAIT_L(n) asm volatile("s_waitcnt lgkmcnt(" #n ")" ::: "memory")
; #define PG8_BAR __builtin_amdgcn_s_barrier()
; #define PG8_SCHED __builtin_amdgcn_sched_barrier(0)
; template <class Epi, class Sched, bool ALIGN_EPI = false, bool SP2 = false>
; __device__ __forceinline__ void gemm_phase(PG8_LAS unsigned char* lds, const Gemm g, const Sched& S, const Epi& E) {
;     ...
;             PG8_WAIT_V(8); PG8_WAIT_L(0); PG8_BAR; PG8_MMA(0, 0, At, B0); PG8_MMA(0, 1, At, B1); PG8_BAR; PG8_SCHED;
;             PG8_LDA(At, 0, 1); PG8_STAGE(PG8_SB(0, 0), b2, voffB); PG8_STAGE(PG8_SB(0, 1), b2 + hstep, voffB); PG8_STAGE(PG8_SA(0, 0), a2, voffA);
.Lrj_P1_0:
	s_waitcnt lgkmcnt(0)
	s_barrier
	s_setprio 1
	s_waitcnt lgkmcnt(0)
	v_mfma_f32_16x16x32_bf16 v[124:127], v[128:131], v[202:205], v[124:127]
	v_mfma_f32_16x16x32_bf16 v[104:107], v[136:139], v[210:213], v[104:107]
	v_mfma_f32_16x16x32_bf16 v[92:95], v[128:131], v[218:221], v[92:95]
	v_mfma_f32_16x16x32_bf16 v[72:75], v[136:139], v[230:233], v[72:75]
	v_mfma_f32_16x16x32_bf16 v[108:111], v[128:131], v[210:213], v[108:111]
	v_mfma_f32_16x16x32_bf16 v[120:123], v[136:139], v[202:205], v[120:123]
	v_mfma_f32_16x16x32_bf16 v[76:79], v[128:131], v[230:233], v[76:79]
	v_mfma_f32_16x16x32_bf16 v[88:91], v[136:139], v[218:221], v[88:91]
	v_mfma_f32_16x16x32_bf16 v[124:127], v[132:135], v[206:209], v[124:127]
	v_mfma_f32_16x16x32_bf16 v[104:107], v[140:143], v[214:217], v[104:107]
	v_mfma_f32_16x16x32_bf16 v[92:95], v[132:135], v[222:225], v[92:95]
	v_mfma_f32_16x16x32_bf16 v[72:75], v[140:143], v[234:237], v[72:75]
	v_mfma_f32_16x16x32_bf16 v[108:111], v[132:135], v[214:217], v[108:111]
	v_mfma_f32_16x16x32_bf16 v[120:123], v[140:143], v[206:209], v[120:123]
	v_mfma_f32_16x16x32_bf16 v[76:79], v[132:135], v[234:237], v[76:79]
	v_mfma_f32_16x16x32_bf16 v[88:91], v[140:143], v[222:225], v[88:91]
	s_setprio 0
	s_setprio 1
	v_mfma_f32_16x16x32_bf16 v[116:119], v[144:147], v[202:205], v[116:119]
	v_mfma_f32_16x16x32_bf16 v[96:99], v[184:187], v[210:213], v[96:99]
	v_mfma_f32_16x16x32_bf16 v[84:87], v[144:147], v[218:221], v[84:87]
	v_mfma_f32_16x16x32_bf16 v[64:67], v[184:187], v[230:233], v[64:67]
	v_mfma_f32_16x16x32_bf16 v[100:103], v[144:147], v[210:213], v[100:103]
	v_mfma_f32_16x16x32_bf16 v[112:115], v[184:187], v[202:205], v[112:115]
	v_mfma_f32_16x16x32_bf16 v[68:71], v[144:147], v[230:233], v[68:71]
	v_mfma_f32_16x16x32_bf16 v[80:83], v[184:187], v[218:221], v[80:83]
	v_mfma_f32_16x16x32_bf16 v[116:119], v[148:151], v[206:209], v[116:119]
	v_mfma_f32_16x16x32_bf16 v[96:99], v[188:191], v[214:217], v[96:99]
	v_mfma_f32_16x16x32_bf16 v[84:87], v[148:151], v[222:225], v[84:87]
	v_mfma_f32_16x16x32_bf16 v[64:67], v[188:191], v[234:237], v[64:67]
	v_mfma_f32_16x16x32_bf16 v[100:103], v[148:151], v[214:217], v[100:103]
	v_mfma_f32_16x16x32_bf16 v[112:115], v[188:191], v[206:209], v[112:115]
	v_mfma_f32_16x16x32_bf16 v[68:71], v[148:151], v[234:237], v[68:71]
	v_mfma_f32_16x16x32_bf16 v[80:83], v[188:191], v[222:225], v[80:83]
	s_setprio 0
	s_barrier
	s_add_i32 s29, s33, s74
	v_lshl_add_u64 v[192:193], s[6:7], 0, v[158:159]
	s_mov_b32 m0, s29
	ds_read_b128 v[202:205], v194 offset:16384
	ds_read_b128 v[206:209], v194 offset:17408
	ds_read_b128 v[210:213], v194 offset:18432
	ds_read_b128 v[214:217], v194 offset:19456
	ds_read_b128 v[218:221], v194 offset:20480
	ds_read_b128 v[222:225], v194 offset:21504
	ds_read_b128 v[230:233], v194 offset:22528
	ds_read_b128 v[234:237], v194 offset:23552
	global_load_lds_dwordx4 v[192:193], off
	s_add_i32 m0, s29, 0x2000
	s_add_u32 s38, s6, 0x40000
	v_lshl_add_u64 v[238:239], s[6:7], 0, v[162:163]
	s_addc_u32 s39, s7, 0
	s_add_i32 s29, s83, s74
	global_load_lds_dwordx4 v[238:239], off
	v_lshl_add_u64 v[240:241], s[38:39], 0, v[158:159]
	s_mov_b32 m0, s29
	v_lshl_add_u64 v[242:243], s[8:9], 0, v[160:161]
	global_load_lds_dwordx4 v[240:241], off
	v_lshl_add_u64 v[240:241], s[38:39], 0, v[162:163]
	s_add_i32 m0, s29, 0x2000
	s_nop 0
	global_load_lds_dwordx4 v[240:241], off
	v_lshl_add_u64 v[240:241], s[8:9], 0, v[156:157]
	s_mov_b32 m0, s37
	s_nop 0
	global_load_lds_dwordx4 v[240:241], off
	s_mov_b32 m0, s75
	s_nop 0
	global_load_lds_dwordx4 v[242:243], off
	s_cmp_eq_u32 s99, 1
	s_cbranch_scc1 .Lrw_P1_1
	s_waitcnt vmcnt(8)
	s_branch .Lrj_P1_1

; #define PG8_STAGE(bufoff, gbase, voff) do { _Pragma("unroll") for (int _i = 0; _i < 2; ++_i) \
;         __builtin_amdgcn_global_load_lds((const unsigned*)((const char*)(gbase) + (voff)[_i]), (PG8_LAS unsigned*)(lds + (bufoff) + ldsw + _i * 8192), 16, 0, 0); } while (0)
; #define PG8_LDA(dst, b, h) do { _Pragma("unroll") for (int m = 0; m < 4; ++m) _Pragma("unroll") for (int k = 0; k < 2; ++k) dst[m][k] = *(const PG8_LAS bf16x8*)(lds + PG8_SA(b, h) + aoff + m * 2048 + k * 1024); } while (0)
; #define PG8_LDB(dst, b, h) do { _Pragma("unroll") for (int n = 0; n < 2; ++n) _Pragma("unroll") for (int k = 0; k < 2; ++k) dst[n][k] = *(const PG8_LAS bf16x8*)(lds + PG8_SB(b, h) + boff + n * 2048 + k * 1024); } while (0)
; #define PG8_MMA(ai, bj, At, Bt) do { __builtin_amdgcn_s_setprio(1); _Pragma("unroll") for (int m = 0; m < 4; ++m) _Pragma("unroll") for (int n = 0; n < 2; ++n) _Pragma("unroll") for (int k = 0; k < 2; ++k) \
;         acc[ai][bj][m][n] = __builtin_amdgcn_mfma_f32_16x16x32_bf16(Bt[n][k], At[m][k], acc[ai][bj][m][n], 0, 0, 0); __builtin_amdgcn_s_setprio(0); } while (0)
; #define PG8_WAIT_V(n) asm volatile("s_waitcnt vmcnt(" #n ")" ::: "memory")
; #define PG8_WAIT_L(n) asm volatile("s_waitcnt lgkmcnt(" #n ")" ::: "memory")
; #define PG8_BAR __builtin_amdgcn_s_barrier()
; #define PG8_SCHED __builtin_amdgcn_sched_barrier(0)
; template <class Epi, class Sched, bool ALIGN_EPI = false, bool SP2 = false>
; __device__ __forceinline__ void gemm_phase(PG8_LAS unsigned char* lds, const Gemm g, const Sched& S, const Epi& E) {
;     ...
;             PG8_WAIT_V(8); PG8_WAIT_L(0); PG8_BAR; PG8_MMA(1, 0, At, B0); PG8_MMA(1, 1, At, B1); PG8_BAR; PG8_SCHED;
;             PG8_LDB(B0, 1, 0); PG8_LDB(B1, 1, 1); PG8_SCHED; PG8_LDA(At, 1, 0); PG8_STAGE(PG8_SA(0, 1), a2 + hstep, voffA);
;             PG8_WAIT_V(8); PG8_WAIT_L(0); PG8_BAR; PG8_MMA(0, 0, At, B0); PG8_MMA(0, 1, At, B1); PG8_BAR; PG8_SCHED;
.Lrj_P1_1:
	s_waitcnt lgkmcnt(0)
	s_barrier
	s_setprio 1
	s_waitcnt lgkmcnt(0)
	v_mfma_f32_16x16x32_bf16 v[60:63], v[128:131], v[202:205], v[60:63]
	v_mfma_f32_16x16x32_bf16 v[40:43], v[136:139], v[210:213], v[40:43]
	v_mfma_f32_16x16x32_bf16 v[28:31], v[128:131], v[218:221], v[28:31]
	v_mfma_f32_16x16x32_bf16 v[8:11], v[136:139], v[230:233], v[8:11]
	v_mfma_f32_16x16x32_bf16 v[44:47], v[128:131], v[210:213], v[44:47]
	v_mfma_f32_16x16x32_bf16 v[56:59], v[136:139], v[202:205], v[56:59]
	v_mfma_f32_16x16x32_bf16 v[12:15], v[128:131], v[230:233], v[12:15]
	v_mfma_f32_16x16x32_bf16 v[24:27], v[136:139], v[218:221], v[24:27]
	v_mfma_f32_16x16x32_bf16 v[60:63], v[132:135], v[206:209], v[60:63]
	v_mfma_f32_16x16x32_bf16 v[40:43], v[140:143], v[214:217], v[40:43]
	v_mfma_f32_16x16x32_bf16 v[28:31], v[132:135], v[222:225], v[28:31]
	v_mfma_f32_16x16x32_bf16 v[8:11], v[140:143], v[234:237], v[8:11]
	v_mfma_f32_16x16x32_bf16 v[44:47], v[132:135], v[214:217], v[44:47]
	v_mfma_f32_16x16x32_bf16 v[56:59], v[140:143], v[206:209], v[56:59]
	v_mfma_f32_16x16x32_bf16 v[12:15], v[132:135], v[234:237], v[12:15]
	v_mfma_f32_16x16x32_bf16 v[24:27], v[140:143], v[222:225], v[24:27]
	s_setprio 0
	s_setprio 1
	v_mfma_f32_16x16x32_bf16 v[52:55], v[144:147], v[202:205], v[52:55]
	v_mfma_f32_16x16x32_bf16 v[32:35], v[184:187], v[210:213], v[32:35]
	v_mfma_f32_16x16x32_bf16 v[20:23], v[144:147], v[218:221], v[20:23]
	v_mfma_f32_16x16x32_bf16 v[0:3], v[184:187], v[230:233], v[0:3]
	v_mfma_f32_16x16x32_bf16 v[36:39], v[144:147], v[210:213], v[36:39]
	v_mfma_f32_16x16x32_bf16 v[48:51], v[184:187], v[202:205], v[48:51]
	v_mfma_f32_16x16x32_bf16 v[4:7], v[144:147], v[230:233], v[4:7]
	v_mfma_f32_16x16x32_bf16 v[16:19], v[184:187], v[218:221], v[16:19]
	v_mfma_f32_16x16x32_bf16 v[52:55], v[148:151], v[206:209], v[52:55]
	v_mfma_f32_16x16x32_bf16 v[32:35], v[188:191], v[214:217], v[32:35]
	v_mfma_f32_16x16x32_bf16 v[20:23], v[148:151], v[222:225], v[20:23]
	v_mfma_f32_16x16x32_bf16 v[0:3], v[188:191], v[234:237], v[0:3]
	v_mfma_f32_16x16x32_bf16 v[36:39], v[148:151], v[214:217], v[36:39]
	v_mfma_f32_16x16x32_bf16 v[48:51], v[188:191], v[206:209], v[48:51]
	v_mfma_f32_16x16x32_bf16 v[4:7], v[148:151], v[234:237], v[4:7]
	v_mfma_f32_16x16x32_bf16 v[16:19], v[188:191], v[222:225], v[16:19]
	s_setprio 0
	s_barrier
	s_add_i32 s29, 0, 0x18000
	s_add_i32 s38, 0, 0x1c000
	v_add_u32_e32 v140, s29, v169
	v_add_u32_e32 v164, s38, v169
	ds_read_b128 v[128:131], v140
	ds_read_b128 v[132:135], v140 offset:1024
	ds_read_b128 v[136:139], v140 offset:2048
	ds_read_b128 v[140:143], v140 offset:3072
	ds_read_b128 v[144:147], v164
	ds_read_b128 v[148:151], v164 offset:1024
	ds_read_b128 v[184:187], v164 offset:2048
	ds_read_b128 v[188:191], v164 offset:3072
	s_add_u32 s8, s8, 0x40000
	s_addc_u32 s9, s9, 0
	s_mov_b32 m0, s76
	v_lshl_add_u64 v[244:245], s[8:9], 0, v[156:157]
	ds_read_b128 v[202:205], v194 offset:32768
	ds_read_b128 v[206:209], v194 offset:33792
	ds_read_b128 v[210:213], v194 offset:34816
	ds_read_b128 v[214:217], v194 offset:35840
	ds_read_b128 v[218:221], v194 offset:36864
	ds_read_b128 v[222:225], v194 offset:37888
	ds_read_b128 v[230:233], v194 offset:38912
	ds_read_b128 v[234:237], v194 offset:39936
	global_load_lds_dwordx4 v[244:245], off
	v_lshl_add_u64 v[244:245], s[8:9], 0, v[160:161]
	s_mov_b32 m0, s77
	s_nop 0
	global_load_lds_dwordx4 v[244:245], off
	s_waitcnt vmcnt(8)
	s_waitcnt lgkmcnt(0)
	s_barrier
	s_setprio 1
	s_waitcnt lgkmcnt(0)
	v_mfma_f32_16x16x32_bf16 v[124:127], v[128:131], v[202:205], v[124:127]
	v_mfma_f32_16x16x32_bf16 v[104:107], v[136:139], v[210:213], v[104:107]
	v_mfma_f32_16x16x32_bf16 v[92:95], v[128:131], v[218:221], v[92:95]
	v_mfma_f32_16x16x32_bf16 v[72:75], v[136:139], v[230:233], v[72:75]
	v_mfma_f32_16x16x32_bf16 v[108:111], v[128:131], v[210:213], v[108:111]
	v_mfma_f32_16x16x32_bf16 v[120:123], v[136:139], v[202:205], v[120:123]
	v_mfma_f32_16x16x32_bf16 v[76:79], v[128:131], v[230:233], v[76:79]
	v_mfma_f32_16x16x32_bf16 v[88:91], v[136:139], v[218:221], v[88:91]
	v_mfma_f32_16x16x32_bf16 v[124:127], v[132:135], v[206:209], v[124:127]
	v_mfma_f32_16x16x32_bf16 v[104:107], v[140:143], v[214:217], v[104:107]
	v_mfma_f32_16x16x32_bf16 v[92:95], v[132:135], v[222:225], v[92:95]
	v_mfma_f32_16x16x32_bf16 v[72:75], v[140:143], v[234:237], v[72:75]
	v_mfma_f32_16x16x32_bf16 v[108:111], v[132:135], v[214:217], v[108:111]
	v_mfma_f32_16x16x32_bf16 v[120:123], v[140:143], v[206:209], v[120:123]
	v_mfma_f32_16x16x32_bf16 v[76:79], v[132:135], v[234:237], v[76:79]
	v_mfma_f32_16x16x32_bf16 v[88:91], v[140:143], v[222:225], v[88:91]
	s_setprio 0
	s_setprio 1
	v_mfma_f32_16x16x32_bf16 v[116:119], v[144:147], v[202:205], v[116:119]
	v_mfma_f32_16x16x32_bf16 v[96:99], v[184:187], v[210:213], v[96:99]
	v_mfma_f32_16x16x32_bf16 v[84:87], v[144:147], v[218:221], v[84:87]
	v_mfma_f32_16x16x32_bf16 v[64:67], v[184:187], v[230:233], v[64:67]
	v_mfma_f32_16x16x32_bf16 v[100:103], v[144:147], v[210:213], v[100:103]
	v_mfma_f32_16x16x32_bf16 v[112:115], v[184:187], v[202:205], v[112:115]
	v_mfma_f32_16x16x32_bf16 v[68:71], v[144:147], v[230:233], v[68:71]
	v_mfma_f32_16x16x32_bf16 v[80:83], v[184:187], v[218:221], v[80:83]
	v_mfma_f32_16x16x32_bf16 v[116:119], v[148:151], v[206:209], v[116:119]
	v_mfma_f32_16x16x32_bf16 v[96:99], v[188:191], v[214:217], v[96:99]
	v_mfma_f32_16x16x32_bf16 v[84:87], v[148:151], v[222:225], v[84:87]
	v_mfma_f32_16x16x32_bf16 v[64:67], v[188:191], v[234:237], v[64:67]
	v_mfma_f32_16x16x32_bf16 v[100:103], v[148:151], v[214:217], v[100:103]
	v_mfma_f32_16x16x32_bf16 v[112:115], v[188:191], v[206:209], v[112:115]
	v_mfma_f32_16x16x32_bf16 v[68:71], v[148:151], v[234:237], v[68:71]
	v_mfma_f32_16x16x32_bf16 v[80:83], v[188:191], v[222:225], v[80:83]
	s_setprio 0
	s_barrier
; #define PG8_STAGE(bufoff, gbase, voff) do { _Pragma("unroll") for (int _i = 0; _i < 2; ++_i) \
;         __builtin_amdgcn_global_load_lds((const unsigned*)((const char*)(gbase) + (voff)[_i]), (PG8_LAS unsigned*)(lds + (bufoff) + ldsw + _i * 8192), 16, 0, 0); } while (0)
; #define PG8_LDA(dst, b, h) do { _Pragma("unroll") for (int m = 0; m < 4; ++m) _Pragma("unroll") for (int k = 0; k < 2; ++k) dst[m][k] = *(const PG8_LAS bf16x8*)(lds + PG8_SA(b, h) + aoff + m * 2048 + k * 1024); } while (0)
; #define PG8_MMA(ai, bj, At, Bt) do { __builtin_amdgcn_s_setprio(1); _Pragma("unroll") for (int m = 0; m < 4; ++m) _Pragma("unroll") for (int n = 0; n < 2; ++n) _Pragma("unroll") for (int k = 0; k < 2; ++k) \
;         acc[ai][bj][m][n] = __builtin_amdgcn_mfma_f32_16x16x32_bf16(Bt[n][k], At[m][k], acc[ai][bj][m][n], 0, 0, 0); __builtin_amdgcn_s_setprio(0); } while (0)
; #define PG8_WAIT_V(n) asm volatile("s_waitcnt vmcnt(" #n ")" ::: "memory")
; #define PG8_WAIT_L(n) asm volatile("s_waitcnt lgkmcnt(" #n ")" ::: "memory")
; #define PG8_BAR __builtin_amdgcn_s_barrier()
; #define PG8_SCHED __builtin_amdgcn_sched_barrier(0)
; template <class Epi, class Sched, bool ALIGN_EPI = false, bool SP2 = false>
; __device__ __forceinline__ void gemm_phase(PG8_LAS unsigned char* lds, const Gemm g, const Sched& S, const Epi& E) {
;     ...
;             PG8_LDA(At, 1, 1); PG8_STAGE(PG8_SB(1, 0), b3, voffB); PG8_STAGE(PG8_SB(1, 1), b3 + hstep, voffB); PG8_STAGE(PG8_SA(1, 0), a3, voffA);
;             PG8_WAIT_V(8); PG8_WAIT_L(0); PG8_BAR; PG8_MMA(1, 0, At, B0); PG8_MMA(1, 1, At, B1); PG8_BAR; PG8_SCHED;
;     ...
;         if constexpr (ALIGN_EPI) { if (wr == 0) PG8_BAR; }
	s_add_i32 s8, s29, s74
	v_lshl_add_u64 v[192:193], v[192:193], 0, s[22:23]
	s_mov_b32 m0, s8
	ds_read_b128 v[202:205], v194 offset:49152
	ds_read_b128 v[206:209], v194 offset:50176
	ds_read_b128 v[210:213], v194 offset:51200
	ds_read_b128 v[214:217], v194 offset:52224
	ds_read_b128 v[218:221], v194 offset:53248
	ds_read_b128 v[222:225], v194 offset:54272
	ds_read_b128 v[230:233], v194 offset:55296
	ds_read_b128 v[234:237], v194 offset:56320
	global_load_lds_dwordx4 v[192:193], off
	s_add_i32 m0, s8, 0x2000
	s_add_u32 s6, s6, 0x40080
	v_lshl_add_u64 v[192:193], v[238:239], 0, s[22:23]
	s_addc_u32 s7, s7, 0
	s_add_i32 s8, s38, s74
	global_load_lds_dwordx4 v[192:193], off
	v_lshl_add_u64 v[192:193], s[6:7], 0, v[158:159]
	s_mov_b32 m0, s8
	s_nop 0
	global_load_lds_dwordx4 v[192:193], off
	v_lshl_add_u64 v[192:193], s[6:7], 0, v[162:163]
	s_add_i32 m0, s8, 0x2000
	s_nop 0
	global_load_lds_dwordx4 v[192:193], off
	v_lshl_add_u64 v[192:193], v[240:241], 0, s[22:23]
	s_mov_b32 m0, s95
	s_nop 0
	global_load_lds_dwordx4 v[192:193], off
	v_lshl_add_u64 v[192:193], v[242:243], 0, s[22:23]
	s_mov_b32 m0, s96
	s_nop 0
	global_load_lds_dwordx4 v[192:193], off
	s_waitcnt vmcnt(8)
	s_waitcnt lgkmcnt(0)
	s_barrier
	s_setprio 1
	s_waitcnt lgkmcnt(0)
	v_mfma_f32_16x16x32_bf16 v[60:63], v[128:131], v[202:205], v[60:63]
	v_mfma_f32_16x16x32_bf16 v[40:43], v[136:139], v[210:213], v[40:43]
	v_mfma_f32_16x16x32_bf16 v[28:31], v[128:131], v[218:221], v[28:31]
	v_mfma_f32_16x16x32_bf16 v[8:11], v[136:139], v[230:233], v[8:11]
	v_mfma_f32_16x16x32_bf16 v[44:47], v[128:131], v[210:213], v[44:47]
	v_mfma_f32_16x16x32_bf16 v[56:59], v[136:139], v[202:205], v[56:59]
	v_mfma_f32_16x16x32_bf16 v[12:15], v[128:131], v[230:233], v[12:15]
	v_mfma_f32_16x16x32_bf16 v[24:27], v[136:139], v[218:221], v[24:27]
	v_mfma_f32_16x16x32_bf16 v[60:63], v[132:135], v[206:209], v[60:63]
	v_mfma_f32_16x16x32_bf16 v[40:43], v[140:143], v[214:217], v[40:43]
	v_mfma_f32_16x16x32_bf16 v[28:31], v[132:135], v[222:225], v[28:31]
	v_mfma_f32_16x16x32_bf16 v[8:11], v[140:143], v[234:237], v[8:11]
	v_mfma_f32_16x16x32_bf16 v[44:47], v[132:135], v[214:217], v[44:47]
	v_mfma_f32_16x16x32_bf16 v[56:59], v[140:143], v[206:209], v[56:59]
	v_mfma_f32_16x16x32_bf16 v[12:15], v[132:135], v[234:237], v[12:15]
	v_mfma_f32_16x16x32_bf16 v[24:27], v[140:143], v[222:225], v[24:27]
	s_setprio 0
	s_setprio 1
	v_mfma_f32_16x16x32_bf16 v[52:55], v[144:147], v[202:205], v[52:55]
	v_mfma_f32_16x16x32_bf16 v[32:35], v[184:187], v[210:213], v[32:35]
	v_mfma_f32_16x16x32_bf16 v[20:23], v[144:147], v[218:221], v[20:23]
	v_mfma_f32_16x16x32_bf16 v[0:3], v[184:187], v[230:233], v[0:3]
	v_mfma_f32_16x16x32_bf16 v[36:39], v[144:147], v[210:213], v[36:39]
	v_mfma_f32_16x16x32_bf16 v[48:51], v[184:187], v[202:205], v[48:51]
	v_mfma_f32_16x16x32_bf16 v[4:7], v[144:147], v[230:233], v[4:7]
	v_mfma_f32_16x16x32_bf16 v[16:19], v[184:187], v[218:221], v[16:19]
	v_mfma_f32_16x16x32_bf16 v[52:55], v[148:151], v[206:209], v[52:55]
	v_mfma_f32_16x16x32_bf16 v[32:35], v[188:191], v[214:217], v[32:35]
	v_mfma_f32_16x16x32_bf16 v[20:23], v[148:151], v[222:225], v[20:23]
	v_mfma_f32_16x16x32_bf16 v[0:3], v[188:191], v[234:237], v[0:3]
	v_mfma_f32_16x16x32_bf16 v[36:39], v[148:151], v[214:217], v[36:39]
	v_mfma_f32_16x16x32_bf16 v[48:51], v[188:191], v[206:209], v[48:51]
	v_mfma_f32_16x16x32_bf16 v[4:7], v[148:151], v[234:237], v[4:7]
	v_mfma_f32_16x16x32_bf16 v[16:19], v[188:191], v[222:225], v[16:19]
	s_setprio 0
	s_barrier
	s_mov_b32 s99, 0
	s_add_i32 s27, s27, 2
	s_add_u32 s4, s4, 0x100
	s_addc_u32 s5, s5, 0
	s_add_u32 s24, s24, 0x100
	s_addc_u32 s25, s25, 0
	s_cmp_gt_u32 s27, 13
	s_cbranch_scc0 .LBB0_121
	s_and_b64 vcc, exec, s[70:71]
	s_cbranch_vccz .LBB0_124
	s_barrier

; #define PG8_STAGE(bufoff, gbase, voff) do { _Pragma("unroll") for (int _i = 0; _i < 2; ++_i) \
;         __builtin_amdgcn_global_load_lds((const unsigned*)((const char*)(gbase) + (voff)[_i]), (PG8_LAS unsigned*)(lds + (bufoff) + ldsw + _i * 8192), 16, 0, 0); } while (0)
; #define PG8_LDA(dst, b, h) do { _Pragma("unroll") for (int m = 0; m < 4; ++m) _Pragma("unroll") for (int k = 0; k < 2; ++k) dst[m][k] = *(const PG8_LAS bf16x8*)(lds + PG8_SA(b, h) + aoff + m * 2048 + k * 1024); } while (0)
; #define PG8_MMA(ai, bj, At, Bt) do { __builtin_amdgcn_s_setprio(1); _Pragma("unroll") for (int m = 0; m < 4; ++m) _Pragma("unroll") for (int n = 0; n < 2; ++n) _Pragma("unroll") for (int k = 0; k < 2; ++k) \
;         acc[ai][bj][m][n] = __builtin_amdgcn_mfma_f32_16x16x32_bf16(Bt[n][k], At[m][k], acc[ai][bj][m][n], 0, 0, 0); __builtin_amdgcn_s_setprio(0); } while (0)
; #define PG8_WAIT_V(n) asm volatile("s_waitcnt vmcnt(" #n ")" ::: "memory")
; #define PG8_WAIT_L(n) asm volatile("s_waitcnt lgkmcnt(" #n ")" ::: "memory")
; #define PG8_BAR __builtin_amdgcn_s_barrier()
; #define PG8_SCHED __builtin_amdgcn_sched_barrier(0)
; template <class Epi, class Sched, bool ALIGN_EPI = false, bool SP2 = false>
; __device__ __forceinline__ void gemm_phase(PG8_LAS unsigned char* lds, const Gemm g, const Sched& S, const Epi& E) {
;     ...
;             PG8_WAIT_V(8); PG8_WAIT_L(0); PG8_BAR; PG8_MMA(0, 0, At, B0); PG8_MMA(0, 1, At, B1); PG8_BAR; PG8_SCHED;
;             PG8_LDA(At, 0, 1); PG8_STAGE(PG8_SB(0, 0), b2, voffB); PG8_STAGE(PG8_SB(0, 1), b2 + hstep, voffB); PG8_STAGE(PG8_SA(0, 0), a2, voffA);
.Lrj_P3a_0:
	s_waitcnt lgkmcnt(0)
	s_barrier
	s_setprio 1
	s_waitcnt lgkmcnt(0)
	v_mfma_f32_16x16x32_bf16 v[124:127], v[144:147], v[184:187], v[124:127]
	v_mfma_f32_16x16x32_bf16 v[104:107], v[160:163], v[192:195], v[104:107]
	v_mfma_f32_16x16x32_bf16 v[96:99], v[144:147], v[200:203], v[96:99]
	v_mfma_f32_16x16x32_bf16 v[72:75], v[160:163], v[208:211], v[72:75]
	v_mfma_f32_16x16x32_bf16 v[112:115], v[144:147], v[192:195], v[112:115]
	v_mfma_f32_16x16x32_bf16 v[120:123], v[160:163], v[184:187], v[120:123]
	v_mfma_f32_16x16x32_bf16 v[80:83], v[144:147], v[208:211], v[80:83]
	v_mfma_f32_16x16x32_bf16 v[88:91], v[160:163], v[200:203], v[88:91]
	v_mfma_f32_16x16x32_bf16 v[124:127], v[156:159], v[188:191], v[124:127]
	v_mfma_f32_16x16x32_bf16 v[104:107], v[164:167], v[196:199], v[104:107]
	v_mfma_f32_16x16x32_bf16 v[96:99], v[156:159], v[204:207], v[96:99]
	v_mfma_f32_16x16x32_bf16 v[72:75], v[164:167], v[212:215], v[72:75]
	v_mfma_f32_16x16x32_bf16 v[112:115], v[156:159], v[196:199], v[112:115]
	v_mfma_f32_16x16x32_bf16 v[120:123], v[164:167], v[188:191], v[120:123]
	v_mfma_f32_16x16x32_bf16 v[80:83], v[156:159], v[212:215], v[80:83]
	v_mfma_f32_16x16x32_bf16 v[88:91], v[164:167], v[204:207], v[88:91]
	s_setprio 0
	s_setprio 1
	v_mfma_f32_16x16x32_bf16 v[116:119], v[168:171], v[184:187], v[116:119]
	v_mfma_f32_16x16x32_bf16 v[92:95], v[176:179], v[192:195], v[92:95]
	v_mfma_f32_16x16x32_bf16 v[84:87], v[168:171], v[200:203], v[84:87]
	v_mfma_f32_16x16x32_bf16 v[64:67], v[176:179], v[208:211], v[64:67]
	v_mfma_f32_16x16x32_bf16 v[100:103], v[168:171], v[192:195], v[100:103]
	v_mfma_f32_16x16x32_bf16 v[108:111], v[176:179], v[184:187], v[108:111]
	v_mfma_f32_16x16x32_bf16 v[68:71], v[168:171], v[208:211], v[68:71]
	v_mfma_f32_16x16x32_bf16 v[76:79], v[176:179], v[200:203], v[76:79]
	v_mfma_f32_16x16x32_bf16 v[116:119], v[172:175], v[188:191], v[116:119]
	v_mfma_f32_16x16x32_bf16 v[92:95], v[180:183], v[196:199], v[92:95]
	v_mfma_f32_16x16x32_bf16 v[84:87], v[172:175], v[204:207], v[84:87]
	v_mfma_f32_16x16x32_bf16 v[64:67], v[180:183], v[212:215], v[64:67]
	v_mfma_f32_16x16x32_bf16 v[100:103], v[172:175], v[196:199], v[100:103]
	v_mfma_f32_16x16x32_bf16 v[108:111], v[180:183], v[188:191], v[108:111]
	v_mfma_f32_16x16x32_bf16 v[68:71], v[172:175], v[212:215], v[68:71]
	v_mfma_f32_16x16x32_bf16 v[76:79], v[180:183], v[204:207], v[76:79]
	s_setprio 0
	s_barrier
	s_add_i32 s75, s67, s43
	v_lshl_add_u64 v[148:149], s[38:39], 0, v[132:133]
	s_mov_b32 m0, s75
	ds_read_b128 v[184:187], v155 offset:16384
	ds_read_b128 v[188:191], v155 offset:17408
	ds_read_b128 v[192:195], v155 offset:18432
	ds_read_b128 v[196:199], v155 offset:19456
	ds_read_b128 v[200:203], v155 offset:20480
	ds_read_b128 v[204:207], v155 offset:21504
	ds_read_b128 v[208:211], v155 offset:22528
	ds_read_b128 v[212:215], v155 offset:23552
	global_load_lds_dwordx4 v[148:149], off
	s_add_i32 m0, s75, 0x2000
	s_add_u32 s76, s38, 0x20000
	v_lshl_add_u64 v[216:217], s[38:39], 0, v[128:129]
	s_addc_u32 s77, s39, 0
	s_add_i32 s75, s68, s43
	global_load_lds_dwordx4 v[216:217], off
	v_lshl_add_u64 v[218:219], s[76:77], 0, v[132:133]
	s_mov_b32 m0, s75
	v_lshl_add_u64 v[220:221], s[40:41], 0, v[130:131]
	global_load_lds_dwordx4 v[218:219], off
	v_lshl_add_u64 v[218:219], s[76:77], 0, v[128:129]
	s_add_i32 m0, s75, 0x2000
	s_nop 0
	global_load_lds_dwordx4 v[218:219], off
	v_lshl_add_u64 v[218:219], s[40:41], 0, v[134:135]
	s_mov_b32 m0, s35
	s_nop 0
	global_load_lds_dwordx4 v[218:219], off
	s_mov_b32 m0, s52
	s_nop 0
	global_load_lds_dwordx4 v[220:221], off
	s_cmp_eq_u32 s99, 1
	s_cbranch_scc1 .Lrw_P3a_1
	s_waitcnt vmcnt(8)
	s_branch .Lrj_P3a_1

; #define PG8_STAGE(bufoff, gbase, voff) do { _Pragma("unroll") for (int _i = 0; _i < 2; ++_i) \
;         __builtin_amdgcn_global_load_lds((const unsigned*)((const char*)(gbase) + (voff)[_i]), (PG8_LAS unsigned*)(lds + (bufoff) + ldsw + _i * 8192), 16, 0, 0); } while (0)
; #define PG8_LDA(dst, b, h) do { _Pragma("unroll") for (int m = 0; m < 4; ++m) _Pragma("unroll") for (int k = 0; k < 2; ++k) dst[m][k] = *(const PG8_LAS bf16x8*)(lds + PG8_SA(b, h) + aoff + m * 2048 + k * 1024); } while (0)
; #define PG8_LDB(dst, b, h) do { _Pragma("unroll") for (int n = 0; n < 2; ++n) _Pragma("unroll") for (int k = 0; k < 2; ++k) dst[n][k] = *(const PG8_LAS bf16x8*)(lds + PG8_SB(b, h) + boff + n * 2048 + k * 1024); } while (0)
; #define PG8_MMA(ai, bj, At, Bt) do { __builtin_amdgcn_s_setprio(1); _Pragma("unroll") for (int m = 0; m < 4; ++m) _Pragma("unroll") for (int n = 0; n < 2; ++n) _Pragma("unroll") for (int k = 0; k < 2; ++k) \
;         acc[ai][bj][m][n] = __builtin_amdgcn_mfma_f32_16x16x32_bf16(Bt[n][k], At[m][k], acc[ai][bj][m][n], 0, 0, 0); __builtin_amdgcn_s_setprio(0); } while (0)
; #define PG8_WAIT_V(n) asm volatile("s_waitcnt vmcnt(" #n ")" ::: "memory")
; #define PG8_WAIT_L(n) asm volatile("s_waitcnt lgkmcnt(" #n ")" ::: "memory")
; #define PG8_BAR __builtin_amdgcn_s_barrier()
; #define PG8_SCHED __builtin_amdgcn_sched_barrier(0)
; template <class Epi, class Sched, bool ALIGN_EPI = false, bool SP2 = false>
; __device__ __forceinline__ void gemm_phase(PG8_LAS unsigned char* lds, const Gemm g, const Sched& S, const Epi& E) {
;     ...
;             PG8_WAIT_V(8); PG8_WAIT_L(0); PG8_BAR; PG8_MMA(1, 0, At, B0); PG8_MMA(1, 1, At, B1); PG8_BAR; PG8_SCHED;
;             PG8_LDB(B0, 1, 0); PG8_LDB(B1, 1, 1); PG8_SCHED; PG8_LDA(At, 1, 0); PG8_STAGE(PG8_SA(0, 1), a2 + hstep, voffA);
;             PG8_WAIT_V(8); PG8_WAIT_L(0); PG8_BAR; PG8_MMA(0, 0, At, B0); PG8_MMA(0, 1, At, B1); PG8_BAR; PG8_SCHED;
.Lrj_P3a_1:
	s_waitcnt lgkmcnt(0)
	s_barrier
	s_setprio 1
	s_waitcnt lgkmcnt(0)
	v_mfma_f32_16x16x32_bf16 v[60:63], v[144:147], v[184:187], v[60:63]
	v_mfma_f32_16x16x32_bf16 v[40:43], v[160:163], v[192:195], v[40:43]
	v_mfma_f32_16x16x32_bf16 v[32:35], v[144:147], v[200:203], v[32:35]
	v_mfma_f32_16x16x32_bf16 v[8:11], v[160:163], v[208:211], v[8:11]
	v_mfma_f32_16x16x32_bf16 v[48:51], v[144:147], v[192:195], v[48:51]
	v_mfma_f32_16x16x32_bf16 v[56:59], v[160:163], v[184:187], v[56:59]
	v_mfma_f32_16x16x32_bf16 v[16:19], v[144:147], v[208:211], v[16:19]
	v_mfma_f32_16x16x32_bf16 v[24:27], v[160:163], v[200:203], v[24:27]
	v_mfma_f32_16x16x32_bf16 v[60:63], v[156:159], v[188:191], v[60:63]
	v_mfma_f32_16x16x32_bf16 v[40:43], v[164:167], v[196:199], v[40:43]
	v_mfma_f32_16x16x32_bf16 v[32:35], v[156:159], v[204:207], v[32:35]
	v_mfma_f32_16x16x32_bf16 v[8:11], v[164:167], v[212:215], v[8:11]
	v_mfma_f32_16x16x32_bf16 v[48:51], v[156:159], v[196:199], v[48:51]
	v_mfma_f32_16x16x32_bf16 v[56:59], v[164:167], v[188:191], v[56:59]
	v_mfma_f32_16x16x32_bf16 v[16:19], v[156:159], v[212:215], v[16:19]
	v_mfma_f32_16x16x32_bf16 v[24:27], v[164:167], v[204:207], v[24:27]
	s_setprio 0
	s_setprio 1
	v_mfma_f32_16x16x32_bf16 v[52:55], v[168:171], v[184:187], v[52:55]
	v_mfma_f32_16x16x32_bf16 v[28:31], v[176:179], v[192:195], v[28:31]
	v_mfma_f32_16x16x32_bf16 v[20:23], v[168:171], v[200:203], v[20:23]
	v_mfma_f32_16x16x32_bf16 v[0:3], v[176:179], v[208:211], v[0:3]
	v_mfma_f32_16x16x32_bf16 v[36:39], v[168:171], v[192:195], v[36:39]
	v_mfma_f32_16x16x32_bf16 v[44:47], v[176:179], v[184:187], v[44:47]
	v_mfma_f32_16x16x32_bf16 v[4:7], v[168:171], v[208:211], v[4:7]
	v_mfma_f32_16x16x32_bf16 v[12:15], v[176:179], v[200:203], v[12:15]
	v_mfma_f32_16x16x32_bf16 v[52:55], v[172:175], v[188:191], v[52:55]
	v_mfma_f32_16x16x32_bf16 v[28:31], v[180:183], v[196:199], v[28:31]
	v_mfma_f32_16x16x32_bf16 v[20:23], v[172:175], v[204:207], v[20:23]
	v_mfma_f32_16x16x32_bf16 v[0:3], v[180:183], v[212:215], v[0:3]
	v_mfma_f32_16x16x32_bf16 v[36:39], v[172:175], v[196:199], v[36:39]
	v_mfma_f32_16x16x32_bf16 v[44:47], v[180:183], v[188:191], v[44:47]
	v_mfma_f32_16x16x32_bf16 v[4:7], v[172:175], v[212:215], v[4:7]
	v_mfma_f32_16x16x32_bf16 v[12:15], v[180:183], v[204:207], v[12:15]
	s_setprio 0
	s_barrier
	s_add_i32 s75, 0, 0x18000
	s_add_i32 s76, 0, 0x1c000
	v_add_u32_e32 v164, s75, v151
	v_add_u32_e32 v180, s76, v151
	ds_read_b128 v[144:147], v164
	ds_read_b128 v[156:159], v164 offset:1024
	ds_read_b128 v[160:163], v164 offset:2048
	ds_read_b128 v[164:167], v164 offset:3072
	ds_read_b128 v[168:171], v180
	ds_read_b128 v[172:175], v180 offset:1024
	ds_read_b128 v[176:179], v180 offset:2048
	ds_read_b128 v[180:183], v180 offset:3072
	s_add_u32 s40, s40, 0x20000
	s_addc_u32 s41, s41, 0
	s_mov_b32 m0, s53
	v_lshl_add_u64 v[222:223], s[40:41], 0, v[134:135]
	ds_read_b128 v[184:187], v155 offset:32768
	ds_read_b128 v[188:191], v155 offset:33792
	ds_read_b128 v[192:195], v155 offset:34816
	ds_read_b128 v[196:199], v155 offset:35840
	ds_read_b128 v[200:203], v155 offset:36864
	ds_read_b128 v[204:207], v155 offset:37888
	ds_read_b128 v[208:211], v155 offset:38912
	ds_read_b128 v[212:215], v155 offset:39936
	global_load_lds_dwordx4 v[222:223], off
	v_lshl_add_u64 v[222:223], s[40:41], 0, v[130:131]
	s_mov_b32 m0, s60
	s_nop 0
	global_load_lds_dwordx4 v[222:223], off
	s_waitcnt vmcnt(8)
	s_waitcnt lgkmcnt(0)
	s_barrier
	s_setprio 1
	s_waitcnt lgkmcnt(0)
	v_mfma_f32_16x16x32_bf16 v[124:127], v[144:147], v[184:187], v[124:127]
	v_mfma_f32_16x16x32_bf16 v[104:107], v[160:163], v[192:195], v[104:107]
	v_mfma_f32_16x16x32_bf16 v[96:99], v[144:147], v[200:203], v[96:99]
	v_mfma_f32_16x16x32_bf16 v[72:75], v[160:163], v[208:211], v[72:75]
	v_mfma_f32_16x16x32_bf16 v[112:115], v[144:147], v[192:195], v[112:115]
	v_mfma_f32_16x16x32_bf16 v[120:123], v[160:163], v[184:187], v[120:123]
	v_mfma_f32_16x16x32_bf16 v[80:83], v[144:147], v[208:211], v[80:83]
	v_mfma_f32_16x16x32_bf16 v[88:91], v[160:163], v[200:203], v[88:91]
	v_mfma_f32_16x16x32_bf16 v[124:127], v[156:159], v[188:191], v[124:127]
	v_mfma_f32_16x16x32_bf16 v[104:107], v[164:167], v[196:199], v[104:107]
	v_mfma_f32_16x16x32_bf16 v[96:99], v[156:159], v[204:207], v[96:99]
	v_mfma_f32_16x16x32_bf16 v[72:75], v[164:167], v[212:215], v[72:75]
	v_mfma_f32_16x16x32_bf16 v[112:115], v[156:159], v[196:199], v[112:115]
	v_mfma_f32_16x16x32_bf16 v[120:123], v[164:167], v[188:191], v[120:123]
	v_mfma_f32_16x16x32_bf16 v[80:83], v[156:159], v[212:215], v[80:83]
	v_mfma_f32_16x16x32_bf16 v[88:91], v[164:167], v[204:207], v[88:91]
	s_setprio 0
	s_setprio 1
	v_mfma_f32_16x16x32_bf16 v[116:119], v[168:171], v[184:187], v[116:119]
	v_mfma_f32_16x16x32_bf16 v[92:95], v[176:179], v[192:195], v[92:95]
	v_mfma_f32_16x16x32_bf16 v[84:87], v[168:171], v[200:203], v[84:87]
	v_mfma_f32_16x16x32_bf16 v[64:67], v[176:179], v[208:211], v[64:67]
	v_mfma_f32_16x16x32_bf16 v[100:103], v[168:171], v[192:195], v[100:103]
	v_mfma_f32_16x16x32_bf16 v[108:111], v[176:179], v[184:187], v[108:111]
	v_mfma_f32_16x16x32_bf16 v[68:71], v[168:171], v[208:211], v[68:71]
	v_mfma_f32_16x16x32_bf16 v[76:79], v[176:179], v[200:203], v[76:79]
	v_mfma_f32_16x16x32_bf16 v[116:119], v[172:175], v[188:191], v[116:119]
	v_mfma_f32_16x16x32_bf16 v[92:95], v[180:183], v[196:199], v[92:95]
	v_mfma_f32_16x16x32_bf16 v[84:87], v[172:175], v[204:207], v[84:87]
	v_mfma_f32_16x16x32_bf16 v[64:67], v[180:183], v[212:215], v[64:67]
	v_mfma_f32_16x16x32_bf16 v[100:103], v[172:175], v[196:199], v[100:103]
	v_mfma_f32_16x16x32_bf16 v[108:111], v[180:183], v[188:191], v[108:111]
	v_mfma_f32_16x16x32_bf16 v[68:71], v[172:175], v[212:215], v[68:71]
	v_mfma_f32_16x16x32_bf16 v[76:79], v[180:183], v[204:207], v[76:79]
	s_setprio 0
	s_barrier
; #define PG8_STAGE(bufoff, gbase, voff) do { _Pragma("unroll") for (int _i = 0; _i < 2; ++_i) \
;         __builtin_amdgcn_global_load_lds((const unsigned*)((const char*)(gbase) + (voff)[_i]), (PG8_LAS unsigned*)(lds + (bufoff) + ldsw + _i * 8192), 16, 0, 0); } while (0)
; #define PG8_LDA(dst, b, h) do { _Pragma("unroll") for (int m = 0; m < 4; ++m) _Pragma("unroll") for (int k = 0; k < 2; ++k) dst[m][k] = *(const PG8_LAS bf16x8*)(lds + PG8_SA(b, h) + aoff + m * 2048 + k * 1024); } while (0)
; #define PG8_MMA(ai, bj, At, Bt) do { __builtin_amdgcn_s_setprio(1); _Pragma("unroll") for (int m = 0; m < 4; ++m) _Pragma("unroll") for (int n = 0; n < 2; ++n) _Pragma("unroll") for (int k = 0; k < 2; ++k) \
;         acc[ai][bj][m][n] = __builtin_amdgcn_mfma_f32_16x16x32_bf16(Bt[n][k], At[m][k], acc[ai][bj][m][n], 0, 0, 0); __builtin_amdgcn_s_setprio(0); } while (0)
; #define PG8_WAIT_V(n) asm volatile("s_waitcnt vmcnt(" #n ")" ::: "memory")
; #define PG8_WAIT_L(n) asm volatile("s_waitcnt lgkmcnt(" #n ")" ::: "memory")
; #define PG8_BAR __builtin_amdgcn_s_barrier()
; #define PG8_SCHED __builtin_amdgcn_sched_barrier(0)
; template <class Epi, class Sched, bool ALIGN_EPI = false, bool SP2 = false>
; __device__ __forceinline__ void gemm_phase(PG8_LAS unsigned char* lds, const Gemm g, const Sched& S, const Epi& E) {
;     ...
;             PG8_LDA(At, 1, 1); PG8_STAGE(PG8_SB(1, 0), b3, voffB); PG8_STAGE(PG8_SB(1, 1), b3 + hstep, voffB); PG8_STAGE(PG8_SA(1, 0), a3, voffA);
;             PG8_WAIT_V(8); PG8_WAIT_L(0); PG8_BAR; PG8_MMA(1, 0, At, B0); PG8_MMA(1, 1, At, B1); PG8_BAR; PG8_SCHED;
;     ...
;         if constexpr (ALIGN_EPI) { if (wr == 0) PG8_BAR; }
	s_add_i32 s40, s75, s43
	v_lshl_add_u64 v[148:149], v[148:149], 0, s[12:13]
	s_mov_b32 m0, s40
	ds_read_b128 v[184:187], v155 offset:49152
	ds_read_b128 v[188:191], v155 offset:50176
	ds_read_b128 v[192:195], v155 offset:51200
	ds_read_b128 v[196:199], v155 offset:52224
	ds_read_b128 v[200:203], v155 offset:53248
	ds_read_b128 v[204:207], v155 offset:54272
	ds_read_b128 v[208:211], v155 offset:55296
	ds_read_b128 v[212:215], v155 offset:56320
	global_load_lds_dwordx4 v[148:149], off
	s_add_i32 m0, s40, 0x2000
	s_add_u32 s38, s38, 0x20080
	v_lshl_add_u64 v[148:149], v[216:217], 0, s[12:13]
	s_addc_u32 s39, s39, 0
	s_add_i32 s40, s76, s43
	global_load_lds_dwordx4 v[148:149], off
	v_lshl_add_u64 v[148:149], s[38:39], 0, v[132:133]
	s_mov_b32 m0, s40
	s_nop 0
	global_load_lds_dwordx4 v[148:149], off
	v_lshl_add_u64 v[148:149], s[38:39], 0, v[128:129]
	s_add_i32 m0, s40, 0x2000
	s_nop 0
	global_load_lds_dwordx4 v[148:149], off
	v_lshl_add_u64 v[148:149], v[218:219], 0, s[12:13]
	s_mov_b32 m0, s64
	s_nop 0
	global_load_lds_dwordx4 v[148:149], off
	v_lshl_add_u64 v[148:149], v[220:221], 0, s[12:13]
	s_mov_b32 m0, s65
	s_nop 0
	global_load_lds_dwordx4 v[148:149], off
	s_waitcnt vmcnt(8)
	s_waitcnt lgkmcnt(0)
	s_barrier
	s_setprio 1
	s_waitcnt lgkmcnt(0)
	v_mfma_f32_16x16x32_bf16 v[60:63], v[144:147], v[184:187], v[60:63]
	v_mfma_f32_16x16x32_bf16 v[40:43], v[160:163], v[192:195], v[40:43]
	v_mfma_f32_16x16x32_bf16 v[32:35], v[144:147], v[200:203], v[32:35]
	v_mfma_f32_16x16x32_bf16 v[8:11], v[160:163], v[208:211], v[8:11]
	v_mfma_f32_16x16x32_bf16 v[48:51], v[144:147], v[192:195], v[48:51]
	v_mfma_f32_16x16x32_bf16 v[56:59], v[160:163], v[184:187], v[56:59]
	v_mfma_f32_16x16x32_bf16 v[16:19], v[144:147], v[208:211], v[16:19]
	v_mfma_f32_16x16x32_bf16 v[24:27], v[160:163], v[200:203], v[24:27]
	v_mfma_f32_16x16x32_bf16 v[60:63], v[156:159], v[188:191], v[60:63]
	v_mfma_f32_16x16x32_bf16 v[40:43], v[164:167], v[196:199], v[40:43]
	v_mfma_f32_16x16x32_bf16 v[32:35], v[156:159], v[204:207], v[32:35]
	v_mfma_f32_16x16x32_bf16 v[8:11], v[164:167], v[212:215], v[8:11]
	v_mfma_f32_16x16x32_bf16 v[48:51], v[156:159], v[196:199], v[48:51]
	v_mfma_f32_16x16x32_bf16 v[56:59], v[164:167], v[188:191], v[56:59]
	v_mfma_f32_16x16x32_bf16 v[16:19], v[156:159], v[212:215], v[16:19]
	v_mfma_f32_16x16x32_bf16 v[24:27], v[164:167], v[204:207], v[24:27]
	s_setprio 0
	s_setprio 1
	v_mfma_f32_16x16x32_bf16 v[52:55], v[168:171], v[184:187], v[52:55]
	v_mfma_f32_16x16x32_bf16 v[28:31], v[176:179], v[192:195], v[28:31]
	v_mfma_f32_16x16x32_bf16 v[20:23], v[168:171], v[200:203], v[20:23]
	v_mfma_f32_16x16x32_bf16 v[0:3], v[176:179], v[208:211], v[0:3]
	v_mfma_f32_16x16x32_bf16 v[36:39], v[168:171], v[192:195], v[36:39]
	v_mfma_f32_16x16x32_bf16 v[44:47], v[176:179], v[184:187], v[44:47]
	v_mfma_f32_16x16x32_bf16 v[4:7], v[168:171], v[208:211], v[4:7]
	v_mfma_f32_16x16x32_bf16 v[12:15], v[176:179], v[200:203], v[12:15]
	v_mfma_f32_16x16x32_bf16 v[52:55], v[172:175], v[188:191], v[52:55]
	v_mfma_f32_16x16x32_bf16 v[28:31], v[180:183], v[196:199], v[28:31]
	v_mfma_f32_16x16x32_bf16 v[20:23], v[172:175], v[204:207], v[20:23]
	v_mfma_f32_16x16x32_bf16 v[0:3], v[180:183], v[212:215], v[0:3]
	v_mfma_f32_16x16x32_bf16 v[36:39], v[172:175], v[196:199], v[36:39]
	v_mfma_f32_16x16x32_bf16 v[44:47], v[180:183], v[188:191], v[44:47]
	v_mfma_f32_16x16x32_bf16 v[4:7], v[172:175], v[212:215], v[4:7]
	v_mfma_f32_16x16x32_bf16 v[12:15], v[180:183], v[204:207], v[12:15]
	s_setprio 0
	s_barrier
	s_mov_b32 s99, 0
	s_add_i32 s74, s74, 2
	s_add_u32 s36, s36, 0x100
	s_addc_u32 s37, s37, 0
	s_add_u32 s72, s72, 0x100
	s_addc_u32 s73, s73, 0
	s_cmp_gt_u32 s74, 5
	s_cbranch_scc0 .LBB0_1284
	s_and_b64 vcc, exec, s[14:15]
	s_cbranch_vccz .LBB0_1287
	s_barrier

; #define PG8_STAGE(bufoff, gbase, voff) do { _Pragma("unroll") for (int _i = 0; _i < 2; ++_i) \
;         __builtin_amdgcn_global_load_lds((const unsigned*)((const char*)(gbase) + (voff)[_i]), (PG8_LAS unsigned*)(lds + (bufoff) + ldsw + _i * 8192), 16, 0, 0); } while (0)
; #define PG8_LDA(dst, b, h) do { _Pragma("unroll") for (int m = 0; m < 4; ++m) _Pragma("unroll") for (int k = 0; k < 2; ++k) dst[m][k] = *(const PG8_LAS bf16x8*)(lds + PG8_SA(b, h) + aoff + m * 2048 + k * 1024); } while (0)
; #define PG8_LDB(dst, b, h) do { _Pragma("unroll") for (int n = 0; n < 2; ++n) _Pragma("unroll") for (int k = 0; k < 2; ++k) dst[n][k] = *(const PG8_LAS bf16x8*)(lds + PG8_SB(b, h) + boff + n * 2048 + k * 1024); } while (0)
; #define PG8_MMA(ai, bj, At, Bt) do { __builtin_amdgcn_s_setprio(1); _Pragma("unroll") for (int m = 0; m < 4; ++m) _Pragma("unroll") for (int n = 0; n < 2; ++n) _Pragma("unroll") for (int k = 0; k < 2; ++k) \
;         acc[ai][bj][m][n] = __builtin_amdgcn_mfma_f32_16x16x32_bf16(Bt[n][k], At[m][k], acc[ai][bj][m][n], 0, 0, 0); __builtin_amdgcn_s_setprio(0); } while (0)
; #define PG8_WAIT_V(n) asm volatile("s_waitcnt vmcnt(" #n ")" ::: "memory")
; #define PG8_WAIT_L(n) asm volatile("s_waitcnt lgkmcnt(" #n ")" ::: "memory")
; #define PG8_BAR __builtin_amdgcn_s_barrier()
; #define PG8_SCHED __builtin_amdgcn_sched_barrier(0)
; template <class Epi, class Sched, bool ALIGN_EPI = false, bool SP2 = false>
; __device__ __forceinline__ void gemm_phase(PG8_LAS unsigned char* lds, const Gemm g, const Sched& S, const Epi& E) {
;     ...
;             PG8_WAIT_V(8); PG8_WAIT_L(0); PG8_BAR; PG8_MMA(1, 0, At, B0); PG8_MMA(1, 1, At, B1); PG8_BAR; PG8_SCHED;
;             PG8_LDB(B0, 1, 0); PG8_LDB(B1, 1, 1); PG8_SCHED; PG8_LDA(At, 1, 0); PG8_STAGE(PG8_SA(0, 1), a2 + hstep, voffA);
;             PG8_WAIT_V(8); PG8_WAIT_L(0); PG8_BAR; PG8_MMA(0, 0, At, B0); PG8_MMA(0, 1, At, B1); PG8_BAR; PG8_SCHED;
.Lrj_P3b_1:
	s_mov_b32 s99, 0
	s_waitcnt lgkmcnt(0)
	s_barrier
	s_setprio 1
	s_waitcnt lgkmcnt(0)
	v_mfma_f32_16x16x32_bf16 v[140:143], v[0:3], v[60:63], 0
	v_mfma_f32_16x16x32_bf16 v[158:161], v[0:3], v[104:107], 0
	v_mfma_f32_16x16x32_bf16 v[166:169], v[0:3], v[112:115], 0
	v_mfma_f32_16x16x32_bf16 v[0:3], v[0:3], v[120:123], 0
	v_mfma_f32_16x16x32_bf16 v[140:143], v[4:7], v[100:103], v[140:143]
	v_mfma_f32_16x16x32_bf16 v[158:161], v[4:7], v[108:111], v[158:161]
	v_mfma_f32_16x16x32_bf16 v[166:169], v[4:7], v[116:119], v[166:169]
	v_mfma_f32_16x16x32_bf16 v[0:3], v[4:7], v[124:127], v[0:3]
	v_mfma_f32_16x16x32_bf16 v[4:7], v[8:11], v[120:123], 0
	v_mfma_f32_16x16x32_bf16 v[154:157], v[8:11], v[60:63], 0
	v_mfma_f32_16x16x32_bf16 v[162:165], v[8:11], v[104:107], 0
	v_mfma_f32_16x16x32_bf16 v[170:173], v[8:11], v[112:115], 0
	v_mfma_f32_16x16x32_bf16 v[4:7], v[12:15], v[124:127], v[4:7]
	v_mfma_f32_16x16x32_bf16 v[154:157], v[12:15], v[100:103], v[154:157]
	v_mfma_f32_16x16x32_bf16 v[162:165], v[12:15], v[108:111], v[162:165]
	v_mfma_f32_16x16x32_bf16 v[170:173], v[12:15], v[116:119], v[170:173]
	s_setprio 0
	s_setprio 1
	v_mfma_f32_16x16x32_bf16 v[8:11], v[16:19], v[60:63], 0
	v_mfma_f32_16x16x32_bf16 v[12:15], v[24:27], v[60:63], 0
	v_mfma_f32_16x16x32_bf16 v[8:11], v[20:23], v[100:103], v[8:11]
	v_mfma_f32_16x16x32_bf16 v[12:15], v[28:31], v[100:103], v[12:15]
	v_mfma_f32_16x16x32_bf16 v[60:63], v[16:19], v[104:107], 0
	v_mfma_f32_16x16x32_bf16 v[100:103], v[24:27], v[104:107], 0
	v_mfma_f32_16x16x32_bf16 v[104:107], v[16:19], v[112:115], 0
	v_mfma_f32_16x16x32_bf16 v[16:19], v[16:19], v[120:123], 0
	v_mfma_f32_16x16x32_bf16 v[60:63], v[20:23], v[108:111], v[60:63]
	v_mfma_f32_16x16x32_bf16 v[100:103], v[28:31], v[108:111], v[100:103]
	v_mfma_f32_16x16x32_bf16 v[104:107], v[20:23], v[116:119], v[104:107]
	v_mfma_f32_16x16x32_bf16 v[108:111], v[24:27], v[112:115], 0
	v_mfma_f32_16x16x32_bf16 v[16:19], v[20:23], v[124:127], v[16:19]
	v_mfma_f32_16x16x32_bf16 v[20:23], v[24:27], v[120:123], 0
	v_mfma_f32_16x16x32_bf16 v[108:111], v[28:31], v[116:119], v[108:111]
	v_mfma_f32_16x16x32_bf16 v[20:23], v[28:31], v[124:127], v[20:23]
	s_setprio 0
	s_barrier
	s_add_i32 s37, 0, 0x1c000
	v_add_u32_e32 v153, s37, v147
	ds_read_b128 v[24:27], v152
	ds_read_b128 v[28:31], v152 offset:1024
	ds_read_b128 v[112:115], v152 offset:2048
	ds_read_b128 v[116:119], v152 offset:3072
	ds_read_b128 v[120:123], v153
	ds_read_b128 v[124:127], v153 offset:1024
	ds_read_b128 v[174:177], v153 offset:2048
	ds_read_b128 v[178:181], v153 offset:3072
	s_add_u32 s88, s52, 0x10100
	s_addc_u32 s89, s53, 0
	s_mov_b32 m0, s68
	v_lshl_add_u64 v[220:221], s[88:89], 0, v[134:135]
	ds_read_b128 v[182:185], v151 offset:32768
	ds_read_b128 v[186:189], v151 offset:33792
	ds_read_b128 v[190:193], v151 offset:34816
	ds_read_b128 v[194:197], v151 offset:35840
	ds_read_b128 v[198:201], v151 offset:36864
	ds_read_b128 v[202:205], v151 offset:37888
	ds_read_b128 v[206:209], v151 offset:38912
	ds_read_b128 v[210:213], v151 offset:39936
	global_load_lds_dwordx4 v[220:221], off
	v_lshl_add_u64 v[220:221], s[88:89], 0, v[130:131]
	s_mov_b32 m0, s69
	s_nop 0
	global_load_lds_dwordx4 v[220:221], off
	s_waitcnt vmcnt(8)
	s_waitcnt lgkmcnt(0)
	s_barrier
	s_setprio 1
	s_waitcnt lgkmcnt(0)
	v_mfma_f32_16x16x32_bf16 v[64:67], v[24:27], v[182:185], v[64:67]
	v_mfma_f32_16x16x32_bf16 v[76:79], v[112:115], v[190:193], v[76:79]
	v_mfma_f32_16x16x32_bf16 v[80:83], v[24:27], v[198:201], v[80:83]
	v_mfma_f32_16x16x32_bf16 v[92:95], v[112:115], v[206:209], v[92:95]
	v_mfma_f32_16x16x32_bf16 v[72:75], v[24:27], v[190:193], v[72:75]
	v_mfma_f32_16x16x32_bf16 v[68:71], v[112:115], v[182:185], v[68:71]
	v_mfma_f32_16x16x32_bf16 v[88:91], v[24:27], v[206:209], v[88:91]
	v_mfma_f32_16x16x32_bf16 v[84:87], v[112:115], v[198:201], v[84:87]
	v_mfma_f32_16x16x32_bf16 v[64:67], v[28:31], v[186:189], v[64:67]
	v_mfma_f32_16x16x32_bf16 v[76:79], v[116:119], v[194:197], v[76:79]
	v_mfma_f32_16x16x32_bf16 v[80:83], v[28:31], v[202:205], v[80:83]
	v_mfma_f32_16x16x32_bf16 v[92:95], v[116:119], v[210:213], v[92:95]
	v_mfma_f32_16x16x32_bf16 v[72:75], v[28:31], v[194:197], v[72:75]
	v_mfma_f32_16x16x32_bf16 v[68:71], v[116:119], v[186:189], v[68:71]
	v_mfma_f32_16x16x32_bf16 v[88:91], v[28:31], v[210:213], v[88:91]
	v_mfma_f32_16x16x32_bf16 v[84:87], v[116:119], v[202:205], v[84:87]
	s_setprio 0
	s_setprio 1
	v_mfma_f32_16x16x32_bf16 v[96:99], v[120:123], v[182:185], v[96:99]
	v_mfma_f32_16x16x32_bf16 v[40:43], v[174:177], v[190:193], v[40:43]
	v_mfma_f32_16x16x32_bf16 v[44:47], v[120:123], v[198:201], v[44:47]
	v_mfma_f32_16x16x32_bf16 v[56:59], v[174:177], v[206:209], v[56:59]
	v_mfma_f32_16x16x32_bf16 v[36:39], v[120:123], v[190:193], v[36:39]
	v_mfma_f32_16x16x32_bf16 v[32:35], v[174:177], v[182:185], v[32:35]
	v_mfma_f32_16x16x32_bf16 v[52:55], v[120:123], v[206:209], v[52:55]
	v_mfma_f32_16x16x32_bf16 v[48:51], v[174:177], v[198:201], v[48:51]
	v_mfma_f32_16x16x32_bf16 v[96:99], v[124:127], v[186:189], v[96:99]
	v_mfma_f32_16x16x32_bf16 v[40:43], v[178:181], v[194:197], v[40:43]
	v_mfma_f32_16x16x32_bf16 v[44:47], v[124:127], v[202:205], v[44:47]
	v_mfma_f32_16x16x32_bf16 v[56:59], v[178:181], v[210:213], v[56:59]
	v_mfma_f32_16x16x32_bf16 v[36:39], v[124:127], v[194:197], v[36:39]
	v_mfma_f32_16x16x32_bf16 v[32:35], v[178:181], v[186:189], v[32:35]
	v_mfma_f32_16x16x32_bf16 v[52:55], v[124:127], v[210:213], v[52:55]
	v_mfma_f32_16x16x32_bf16 v[48:51], v[178:181], v[202:205], v[48:51]
	s_setprio 0
	s_barrier
; #define PG8_STAGE(bufoff, gbase, voff) do { _Pragma("unroll") for (int _i = 0; _i < 2; ++_i) \
;         __builtin_amdgcn_global_load_lds((const unsigned*)((const char*)(gbase) + (voff)[_i]), (PG8_LAS unsigned*)(lds + (bufoff) + ldsw + _i * 8192), 16, 0, 0); } while (0)
; #define PG8_LDA(dst, b, h) do { _Pragma("unroll") for (int m = 0; m < 4; ++m) _Pragma("unroll") for (int k = 0; k < 2; ++k) dst[m][k] = *(const PG8_LAS bf16x8*)(lds + PG8_SA(b, h) + aoff + m * 2048 + k * 1024); } while (0)
; #define PG8_LDB(dst, b, h) do { _Pragma("unroll") for (int n = 0; n < 2; ++n) _Pragma("unroll") for (int k = 0; k < 2; ++k) dst[n][k] = *(const PG8_LAS bf16x8*)(lds + PG8_SB(b, h) + boff + n * 2048 + k * 1024); } while (0)
; #define PG8_MMA(ai, bj, At, Bt) do { __builtin_amdgcn_s_setprio(1); _Pragma("unroll") for (int m = 0; m < 4; ++m) _Pragma("unroll") for (int n = 0; n < 2; ++n) _Pragma("unroll") for (int k = 0; k < 2; ++k) \
;         acc[ai][bj][m][n] = __builtin_amdgcn_mfma_f32_16x16x32_bf16(Bt[n][k], At[m][k], acc[ai][bj][m][n], 0, 0, 0); __builtin_amdgcn_s_setprio(0); } while (0)
; #define PG8_WAIT_V(n) asm volatile("s_waitcnt vmcnt(" #n ")" ::: "memory")
; #define PG8_WAIT_L(n) asm volatile("s_waitcnt lgkmcnt(" #n ")" ::: "memory")
; #define PG8_BAR __builtin_amdgcn_s_barrier()
; #define PG8_SCHED __builtin_amdgcn_sched_barrier(0)
; template <class Epi, class Sched, bool ALIGN_EPI = false, bool SP2 = false>
; __device__ __forceinline__ void gemm_phase(PG8_LAS unsigned char* lds, const Gemm g, const Sched& S, const Epi& E) {
;     ...
;             PG8_LDB(B0, 0, 0); PG8_LDB(B1, 0, 1); PG8_SCHED; PG8_LDA(At, 0, 0); PG8_STAGE(PG8_SA(1, 1), a1 + hstep, voffA);
;             PG8_WAIT_V(8); PG8_WAIT_L(0); PG8_BAR; PG8_MMA(0, 0, At, B0); PG8_MMA(0, 1, At, B1); PG8_BAR; PG8_SCHED;
;     ...
;             PG8_LDA(At, 1, 1); PG8_STAGE(PG8_SB(1, 0), b3, voffB); PG8_STAGE(PG8_SB(1, 1), b3 + hstep, voffB); PG8_STAGE(PG8_SA(1, 0), a3, voffA);
;             PG8_WAIT_V(8); PG8_WAIT_L(0); PG8_BAR; PG8_MMA(1, 0, At, B0); PG8_MMA(1, 1, At, B1); PG8_BAR; PG8_SCHED;
	s_add_i32 s83, s81, s47
	s_add_i32 s35, s83, 0x2000
	v_lshl_add_u64 v[144:145], v[144:145], 0, s[22:23]
	s_mov_b32 m0, s83
	s_add_u32 s62, s62, 0x10180
	ds_read_b128 v[182:185], v151 offset:49152
	ds_read_b128 v[186:189], v151 offset:50176
	ds_read_b128 v[190:193], v151 offset:51200
	ds_read_b128 v[194:197], v151 offset:52224
	ds_read_b128 v[198:201], v151 offset:53248
	ds_read_b128 v[202:205], v151 offset:54272
	ds_read_b128 v[206:209], v151 offset:55296
	ds_read_b128 v[210:213], v151 offset:56320
	global_load_lds_dwordx4 v[144:145], off
	v_lshl_add_u64 v[144:145], v[214:215], 0, s[22:23]
	s_mov_b32 m0, s35
	s_addc_u32 s63, s63, 0
	s_add_i32 s37, s37, s47
	global_load_lds_dwordx4 v[144:145], off
	v_lshl_add_u64 v[144:145], s[62:63], 0, v[132:133]
	s_mov_b32 m0, s37
	s_nop 0
	global_load_lds_dwordx4 v[144:145], off
	v_lshl_add_u64 v[144:145], s[62:63], 0, v[128:129]
	s_add_i32 s62, s37, 0x2000
	s_mov_b32 m0, s62
	s_nop 0
	global_load_lds_dwordx4 v[144:145], off
	v_lshl_add_u64 v[144:145], v[216:217], 0, s[22:23]
	s_mov_b32 m0, s70
	s_nop 0
	global_load_lds_dwordx4 v[144:145], off
	v_lshl_add_u64 v[144:145], v[218:219], 0, s[22:23]
	s_mov_b32 m0, s71
	s_nop 0
	global_load_lds_dwordx4 v[144:145], off
	s_waitcnt vmcnt(8)
	s_waitcnt lgkmcnt(0)
	s_barrier
	s_setprio 1
	s_waitcnt lgkmcnt(0)
	v_mfma_f32_16x16x32_bf16 v[0:3], v[24:27], v[206:209], v[0:3]
	v_mfma_f32_16x16x32_bf16 v[154:157], v[112:115], v[182:185], v[154:157]
	v_mfma_f32_16x16x32_bf16 v[158:161], v[24:27], v[190:193], v[158:161]
	v_mfma_f32_16x16x32_bf16 v[170:173], v[112:115], v[198:201], v[170:173]
	v_mfma_f32_16x16x32_bf16 v[140:143], v[24:27], v[182:185], v[140:143]
	v_mfma_f32_16x16x32_bf16 v[4:7], v[112:115], v[206:209], v[4:7]
	v_mfma_f32_16x16x32_bf16 v[166:169], v[24:27], v[198:201], v[166:169]
	v_mfma_f32_16x16x32_bf16 v[162:165], v[112:115], v[190:193], v[162:165]
	v_mfma_f32_16x16x32_bf16 v[0:3], v[28:31], v[210:213], v[0:3]
	v_mfma_f32_16x16x32_bf16 v[154:157], v[116:119], v[186:189], v[154:157]
	v_mfma_f32_16x16x32_bf16 v[158:161], v[28:31], v[194:197], v[158:161]
	v_mfma_f32_16x16x32_bf16 v[170:173], v[116:119], v[202:205], v[170:173]
	v_mfma_f32_16x16x32_bf16 v[140:143], v[28:31], v[186:189], v[140:143]
	v_mfma_f32_16x16x32_bf16 v[4:7], v[116:119], v[210:213], v[4:7]
	v_mfma_f32_16x16x32_bf16 v[166:169], v[28:31], v[202:205], v[166:169]
	v_mfma_f32_16x16x32_bf16 v[162:165], v[116:119], v[194:197], v[162:165]
	s_setprio 0
	s_setprio 1
	v_mfma_f32_16x16x32_bf16 v[8:11], v[120:123], v[182:185], v[8:11]
	v_mfma_f32_16x16x32_bf16 v[12:15], v[174:177], v[182:185], v[12:15]
	v_mfma_f32_16x16x32_bf16 v[24:27], v[120:123], v[190:193], v[60:63]
	v_mfma_f32_16x16x32_bf16 v[28:31], v[174:177], v[190:193], v[100:103]
	v_mfma_f32_16x16x32_bf16 v[60:63], v[120:123], v[198:201], v[104:107]
	v_mfma_f32_16x16x32_bf16 v[100:103], v[174:177], v[198:201], v[108:111]
	v_mfma_f32_16x16x32_bf16 v[16:19], v[120:123], v[206:209], v[16:19]
	v_mfma_f32_16x16x32_bf16 v[20:23], v[174:177], v[206:209], v[20:23]
	v_mfma_f32_16x16x32_bf16 v[8:11], v[124:127], v[186:189], v[8:11]
	v_mfma_f32_16x16x32_bf16 v[12:15], v[178:181], v[186:189], v[12:15]
	v_mfma_f32_16x16x32_bf16 v[24:27], v[124:127], v[194:197], v[24:27]
	v_mfma_f32_16x16x32_bf16 v[28:31], v[178:181], v[194:197], v[28:31]
	v_mfma_f32_16x16x32_bf16 v[60:63], v[124:127], v[202:205], v[60:63]
	v_mfma_f32_16x16x32_bf16 v[100:103], v[178:181], v[202:205], v[100:103]
	v_mfma_f32_16x16x32_bf16 v[16:19], v[124:127], v[210:213], v[16:19]
	v_mfma_f32_16x16x32_bf16 v[20:23], v[178:181], v[210:213], v[20:23]
	s_setprio 0
	s_barrier
	ds_read_b128 v[104:107], v149
	ds_read_b128 v[108:111], v149 offset:1024
	ds_read_b128 v[112:115], v149 offset:2048
	ds_read_b128 v[116:119], v149 offset:3072
	ds_read_b128 v[120:123], v150
	ds_read_b128 v[124:127], v150 offset:1024
	ds_read_b128 v[174:177], v150 offset:2048
	ds_read_b128 v[178:181], v150 offset:3072
	s_add_u32 s52, s52, 0x10180
	s_addc_u32 s53, s53, 0
	s_mov_b32 m0, s73
	v_lshl_add_u64 v[144:145], s[52:53], 0, v[134:135]
	ds_read_b128 v[182:185], v151
	ds_read_b128 v[186:189], v151 offset:1024
	ds_read_b128 v[190:193], v151 offset:2048
	ds_read_b128 v[194:197], v151 offset:3072
	ds_read_b128 v[198:201], v151 offset:4096
	ds_read_b128 v[202:205], v151 offset:5120
	ds_read_b128 v[206:209], v151 offset:6144
	ds_read_b128 v[210:213], v151 offset:7168
	global_load_lds_dwordx4 v[144:145], off
	v_lshl_add_u64 v[144:145], s[52:53], 0, v[130:131]
	s_mov_b32 m0, s74
	s_nop 0
	global_load_lds_dwordx4 v[144:145], off
	s_waitcnt vmcnt(8)
	s_waitcnt lgkmcnt(0)
	s_barrier
; #define PG8_STAGE(bufoff, gbase, voff) do { _Pragma("unroll") for (int _i = 0; _i < 2; ++_i) \
;         __builtin_amdgcn_global_load_lds((const unsigned*)((const char*)(gbase) + (voff)[_i]), (PG8_LAS unsigned*)(lds + (bufoff) + ldsw + _i * 8192), 16, 0, 0); } while (0)
; #define PG8_LDA(dst, b, h) do { _Pragma("unroll") for (int m = 0; m < 4; ++m) _Pragma("unroll") for (int k = 0; k < 2; ++k) dst[m][k] = *(const PG8_LAS bf16x8*)(lds + PG8_SA(b, h) + aoff + m * 2048 + k * 1024); } while (0)
; #define PG8_MMA(ai, bj, At, Bt) do { __builtin_amdgcn_s_setprio(1); _Pragma("unroll") for (int m = 0; m < 4; ++m) _Pragma("unroll") for (int n = 0; n < 2; ++n) _Pragma("unroll") for (int k = 0; k < 2; ++k) \
;         acc[ai][bj][m][n] = __builtin_amdgcn_mfma_f32_16x16x32_bf16(Bt[n][k], At[m][k], acc[ai][bj][m][n], 0, 0, 0); __builtin_amdgcn_s_setprio(0); } while (0)
; #define PG8_WAIT_V(n) asm volatile("s_waitcnt vmcnt(" #n ")" ::: "memory")
; #define PG8_WAIT_L(n) asm volatile("s_waitcnt lgkmcnt(" #n ")" ::: "memory")
; #define PG8_BAR __builtin_amdgcn_s_barrier()
; #define PG8_SCHED __builtin_amdgcn_sched_barrier(0)
; template <class Epi, class Sched, bool ALIGN_EPI = false, bool SP2 = false>
; __device__ __forceinline__ void gemm_phase(PG8_LAS unsigned char* lds, const Gemm g, const Sched& S, const Epi& E) {
;     ...
;             PG8_WAIT_V(8); PG8_WAIT_L(0); PG8_BAR; PG8_MMA(0, 0, At, B0); PG8_MMA(0, 1, At, B1); PG8_BAR; PG8_SCHED;
;             PG8_LDA(At, 0, 1); PG8_STAGE(PG8_SB(0, 0), b2, voffB); PG8_STAGE(PG8_SB(0, 1), b2 + hstep, voffB); PG8_STAGE(PG8_SA(0, 0), a2, voffA);
;             PG8_WAIT_V(8); PG8_WAIT_L(0); PG8_BAR; PG8_MMA(1, 0, At, B0); PG8_MMA(1, 1, At, B1); PG8_BAR; PG8_SCHED;
	s_setprio 1
	s_waitcnt lgkmcnt(0)
	v_mfma_f32_16x16x32_bf16 v[64:67], v[104:107], v[182:185], v[64:67]
	v_mfma_f32_16x16x32_bf16 v[68:71], v[112:115], v[182:185], v[68:71]
	v_mfma_f32_16x16x32_bf16 v[72:75], v[104:107], v[190:193], v[72:75]
	v_mfma_f32_16x16x32_bf16 v[76:79], v[112:115], v[190:193], v[76:79]
	v_mfma_f32_16x16x32_bf16 v[80:83], v[104:107], v[198:201], v[80:83]
	v_mfma_f32_16x16x32_bf16 v[84:87], v[112:115], v[198:201], v[84:87]
	v_mfma_f32_16x16x32_bf16 v[88:91], v[104:107], v[206:209], v[88:91]
	v_mfma_f32_16x16x32_bf16 v[64:67], v[108:111], v[186:189], v[64:67]
	v_mfma_f32_16x16x32_bf16 v[68:71], v[116:119], v[186:189], v[68:71]
	v_mfma_f32_16x16x32_bf16 v[72:75], v[108:111], v[194:197], v[72:75]
	v_mfma_f32_16x16x32_bf16 v[76:79], v[116:119], v[194:197], v[76:79]
	v_mfma_f32_16x16x32_bf16 v[80:83], v[108:111], v[202:205], v[80:83]
	v_mfma_f32_16x16x32_bf16 v[84:87], v[116:119], v[202:205], v[84:87]
	v_mfma_f32_16x16x32_bf16 v[214:217], v[108:111], v[210:213], v[88:91]
	v_mfma_f32_16x16x32_bf16 v[88:91], v[112:115], v[206:209], v[92:95]
	v_mfma_f32_16x16x32_bf16 v[218:221], v[116:119], v[210:213], v[88:91]
	s_setprio 0
	s_setprio 1
	v_mfma_f32_16x16x32_bf16 v[88:91], v[120:123], v[182:185], v[96:99]
	v_mfma_f32_16x16x32_bf16 v[32:35], v[174:177], v[182:185], v[32:35]
	v_mfma_f32_16x16x32_bf16 v[36:39], v[120:123], v[190:193], v[36:39]
	v_mfma_f32_16x16x32_bf16 v[40:43], v[174:177], v[190:193], v[40:43]
	v_mfma_f32_16x16x32_bf16 v[44:47], v[120:123], v[198:201], v[44:47]
	v_mfma_f32_16x16x32_bf16 v[48:51], v[174:177], v[198:201], v[48:51]
	v_mfma_f32_16x16x32_bf16 v[52:55], v[120:123], v[206:209], v[52:55]
	v_mfma_f32_16x16x32_bf16 v[56:59], v[174:177], v[206:209], v[56:59]
	v_mfma_f32_16x16x32_bf16 v[96:99], v[124:127], v[186:189], v[88:91]
	v_mfma_f32_16x16x32_bf16 v[32:35], v[178:181], v[186:189], v[32:35]
	v_mfma_f32_16x16x32_bf16 v[36:39], v[124:127], v[194:197], v[36:39]
	v_mfma_f32_16x16x32_bf16 v[40:43], v[178:181], v[194:197], v[40:43]
	v_mfma_f32_16x16x32_bf16 v[44:47], v[124:127], v[202:205], v[44:47]
	v_mfma_f32_16x16x32_bf16 v[48:51], v[178:181], v[202:205], v[48:51]
	v_mfma_f32_16x16x32_bf16 v[52:55], v[124:127], v[210:213], v[52:55]
	v_mfma_f32_16x16x32_bf16 v[56:59], v[178:181], v[210:213], v[56:59]
	s_setprio 0
	s_barrier
	s_mov_b32 m0, s75
	v_lshl_add_u64 v[144:145], s[64:65], 0, v[132:133]
	s_add_u32 s52, s64, 0x10000
	ds_read_b128 v[88:91], v151 offset:16384
	ds_read_b128 v[92:95], v151 offset:17408
	ds_read_b128 v[182:185], v151 offset:18432
	ds_read_b128 v[186:189], v151 offset:19456
	ds_read_b128 v[190:193], v151 offset:20480
	ds_read_b128 v[194:197], v151 offset:21504
	ds_read_b128 v[198:201], v151 offset:22528
	ds_read_b128 v[202:205], v151 offset:23552
	global_load_lds_dwordx4 v[144:145], off
	v_lshl_add_u64 v[248:249], s[64:65], 0, v[128:129]
	s_mov_b32 m0, s76
	s_addc_u32 s53, s65, 0
	global_load_lds_dwordx4 v[248:249], off
	v_lshl_add_u64 v[206:207], s[52:53], 0, v[132:133]
	s_mov_b32 m0, s77
	v_lshl_add_u64 v[250:251], s[66:67], 0, v[134:135]
	global_load_lds_dwordx4 v[206:207], off
	v_lshl_add_u64 v[206:207], s[52:53], 0, v[128:129]
	s_mov_b32 m0, s80
	v_lshl_add_u64 v[252:253], s[66:67], 0, v[130:131]
	global_load_lds_dwordx4 v[206:207], off
	s_mov_b32 m0, s43
	s_nop 0
	global_load_lds_dwordx4 v[250:251], off
	s_mov_b32 m0, s61
	s_nop 0
	global_load_lds_dwordx4 v[252:253], off
	s_waitcnt vmcnt(8)
	s_waitcnt lgkmcnt(0)
	s_barrier
	s_setprio 1
	s_waitcnt lgkmcnt(0)
	v_mfma_f32_16x16x32_bf16 v[0:3], v[104:107], v[198:201], v[0:3]
	v_mfma_f32_16x16x32_bf16 v[154:157], v[112:115], v[88:91], v[154:157]
	v_mfma_f32_16x16x32_bf16 v[158:161], v[104:107], v[182:185], v[158:161]
	v_mfma_f32_16x16x32_bf16 v[170:173], v[112:115], v[190:193], v[170:173]
	v_mfma_f32_16x16x32_bf16 v[140:143], v[104:107], v[88:91], v[140:143]
	v_mfma_f32_16x16x32_bf16 v[4:7], v[112:115], v[198:201], v[4:7]
	v_mfma_f32_16x16x32_bf16 v[166:169], v[104:107], v[190:193], v[166:169]
	v_mfma_f32_16x16x32_bf16 v[162:165], v[112:115], v[182:185], v[162:165]
	v_mfma_f32_16x16x32_bf16 v[0:3], v[108:111], v[202:205], v[0:3]
	v_mfma_f32_16x16x32_bf16 v[154:157], v[116:119], v[92:95], v[154:157]
	v_mfma_f32_16x16x32_bf16 v[158:161], v[108:111], v[186:189], v[158:161]
	v_mfma_f32_16x16x32_bf16 v[170:173], v[116:119], v[194:197], v[170:173]
	v_mfma_f32_16x16x32_bf16 v[140:143], v[108:111], v[92:95], v[140:143]
	v_mfma_f32_16x16x32_bf16 v[4:7], v[116:119], v[202:205], v[4:7]
	v_mfma_f32_16x16x32_bf16 v[166:169], v[108:111], v[194:197], v[166:169]
	v_mfma_f32_16x16x32_bf16 v[162:165], v[116:119], v[186:189], v[162:165]
	s_setprio 0
	s_setprio 1
	v_mfma_f32_16x16x32_bf16 v[8:11], v[120:123], v[88:91], v[8:11]
	v_mfma_f32_16x16x32_bf16 v[206:209], v[124:127], v[92:95], v[8:11]
	v_mfma_f32_16x16x32_bf16 v[8:11], v[174:177], v[88:91], v[12:15]
	v_mfma_f32_16x16x32_bf16 v[210:213], v[178:181], v[92:95], v[8:11]
	v_mfma_f32_16x16x32_bf16 v[8:11], v[120:123], v[182:185], v[24:27]
	v_mfma_f32_16x16x32_bf16 v[222:225], v[124:127], v[186:189], v[8:11]
	v_mfma_f32_16x16x32_bf16 v[8:11], v[174:177], v[182:185], v[28:31]
	v_mfma_f32_16x16x32_bf16 v[182:185], v[178:181], v[186:189], v[8:11]
	v_mfma_f32_16x16x32_bf16 v[8:11], v[120:123], v[190:193], v[60:63]
	v_mfma_f32_16x16x32_bf16 v[186:189], v[124:127], v[194:197], v[8:11]
	v_mfma_f32_16x16x32_bf16 v[8:11], v[174:177], v[190:193], v[100:103]
	v_mfma_f32_16x16x32_bf16 v[190:193], v[178:181], v[194:197], v[8:11]
	v_mfma_f32_16x16x32_bf16 v[8:11], v[120:123], v[198:201], v[16:19]
	v_mfma_f32_16x16x32_bf16 v[194:197], v[124:127], v[202:205], v[8:11]
	v_mfma_f32_16x16x32_bf16 v[8:11], v[174:177], v[198:201], v[20:23]
	v_mfma_f32_16x16x32_bf16 v[174:177], v[178:181], v[202:205], v[8:11]
	s_setprio 0
	s_barrier
; #define PG8_STAGE(bufoff, gbase, voff) do { _Pragma("unroll") for (int _i = 0; _i < 2; ++_i) \
;         __builtin_amdgcn_global_load_lds((const unsigned*)((const char*)(gbase) + (voff)[_i]), (PG8_LAS unsigned*)(lds + (bufoff) + ldsw + _i * 8192), 16, 0, 0); } while (0)
; #define PG8_LDA(dst, b, h) do { _Pragma("unroll") for (int m = 0; m < 4; ++m) _Pragma("unroll") for (int k = 0; k < 2; ++k) dst[m][k] = *(const PG8_LAS bf16x8*)(lds + PG8_SA(b, h) + aoff + m * 2048 + k * 1024); } while (0)
; #define PG8_LDB(dst, b, h) do { _Pragma("unroll") for (int n = 0; n < 2; ++n) _Pragma("unroll") for (int k = 0; k < 2; ++k) dst[n][k] = *(const PG8_LAS bf16x8*)(lds + PG8_SB(b, h) + boff + n * 2048 + k * 1024); } while (0)
; #define PG8_MMA(ai, bj, At, Bt) do { __builtin_amdgcn_s_setprio(1); _Pragma("unroll") for (int m = 0; m < 4; ++m) _Pragma("unroll") for (int n = 0; n < 2; ++n) _Pragma("unroll") for (int k = 0; k < 2; ++k) \
;         acc[ai][bj][m][n] = __builtin_amdgcn_mfma_f32_16x16x32_bf16(Bt[n][k], At[m][k], acc[ai][bj][m][n], 0, 0, 0); __builtin_amdgcn_s_setprio(0); } while (0)
; #define PG8_WAIT_V(n) asm volatile("s_waitcnt vmcnt(" #n ")" ::: "memory")
; #define PG8_WAIT_L(n) asm volatile("s_waitcnt lgkmcnt(" #n ")" ::: "memory")
; #define PG8_BAR __builtin_amdgcn_s_barrier()
; #define PG8_SCHED __builtin_amdgcn_sched_barrier(0)
; template <class Epi, class Sched, bool ALIGN_EPI = false, bool SP2 = false>
; __device__ __forceinline__ void gemm_phase(PG8_LAS unsigned char* lds, const Gemm g, const Sched& S, const Epi& E) {
;     ...
;             PG8_LDB(B0, 1, 0); PG8_LDB(B1, 1, 1); PG8_SCHED; PG8_LDA(At, 1, 0); PG8_STAGE(PG8_SA(0, 1), a2 + hstep, voffA);
;             PG8_WAIT_V(8); PG8_WAIT_L(0); PG8_BAR; PG8_MMA(0, 0, At, B0); PG8_MMA(0, 1, At, B1); PG8_BAR; PG8_SCHED;
;             PG8_LDA(At, 1, 1); PG8_STAGE(PG8_SB(1, 0), b3, voffB); PG8_STAGE(PG8_SB(1, 1), b3 + hstep, voffB); PG8_STAGE(PG8_SA(1, 0), a3, voffA);
;             PG8_WAIT_V(8); PG8_WAIT_L(0); PG8_BAR; PG8_MMA(1, 0, At, B0); PG8_MMA(1, 1, At, B1); PG8_BAR; PG8_SCHED;
;     ...
;         if constexpr (ALIGN_EPI) { if (wr == 0) PG8_BAR; }
	s_nop 4
	ds_read_b128 v[8:11], v152
	ds_read_b128 v[12:15], v152 offset:1024
	ds_read_b128 v[16:19], v152 offset:2048
	ds_read_b128 v[20:23], v152 offset:3072
	ds_read_b128 v[178:181], v153
	ds_read_b128 v[198:201], v153 offset:1024
	ds_read_b128 v[202:205], v153 offset:2048
	ds_read_b128 v[228:231], v153 offset:3072
	s_add_u32 s52, s66, 0x10000
	s_addc_u32 s53, s67, 0
	s_mov_b32 m0, s68
	v_lshl_add_u64 v[88:89], s[52:53], 0, v[134:135]
	ds_read_b128 v[24:27], v151 offset:32768
	ds_read_b128 v[28:31], v151 offset:33792
	ds_read_b128 v[60:63], v151 offset:34816
	ds_read_b128 v[100:103], v151 offset:35840
	ds_read_b128 v[232:235], v151 offset:36864
	ds_read_b128 v[236:239], v151 offset:37888
	ds_read_b128 v[240:243], v151 offset:38912
	ds_read_b128 v[244:247], v151 offset:39936
	global_load_lds_dwordx4 v[88:89], off
	v_lshl_add_u64 v[88:89], s[52:53], 0, v[130:131]
	s_mov_b32 m0, s69
	s_nop 0
	global_load_lds_dwordx4 v[88:89], off
	s_waitcnt vmcnt(8)
	s_waitcnt lgkmcnt(0)
	s_barrier
	s_setprio 1
	s_waitcnt lgkmcnt(0)
	v_mfma_f32_16x16x32_bf16 v[64:67], v[8:11], v[24:27], v[64:67]
	v_mfma_f32_16x16x32_bf16 v[124:127], v[12:15], v[28:31], v[64:67]
	v_mfma_f32_16x16x32_bf16 v[64:67], v[16:19], v[24:27], v[68:71]
	v_mfma_f32_16x16x32_bf16 v[120:123], v[20:23], v[28:31], v[64:67]
	v_mfma_f32_16x16x32_bf16 v[64:67], v[8:11], v[60:63], v[72:75]
	v_mfma_f32_16x16x32_bf16 v[108:111], v[12:15], v[100:103], v[64:67]
	v_mfma_f32_16x16x32_bf16 v[64:67], v[16:19], v[60:63], v[76:79]
	v_mfma_f32_16x16x32_bf16 v[104:107], v[20:23], v[100:103], v[64:67]
	v_mfma_f32_16x16x32_bf16 v[64:67], v[8:11], v[232:235], v[80:83]
	v_mfma_f32_16x16x32_bf16 v[92:95], v[12:15], v[236:239], v[64:67]
	v_mfma_f32_16x16x32_bf16 v[64:67], v[16:19], v[232:235], v[84:87]
	v_mfma_f32_16x16x32_bf16 v[88:91], v[20:23], v[236:239], v[64:67]
	v_mfma_f32_16x16x32_bf16 v[64:67], v[8:11], v[240:243], v[214:217]
	v_mfma_f32_16x16x32_bf16 v[76:79], v[12:15], v[244:247], v[64:67]
	v_mfma_f32_16x16x32_bf16 v[64:67], v[16:19], v[240:243], v[218:221]
	v_mfma_f32_16x16x32_bf16 v[72:75], v[20:23], v[244:247], v[64:67]
	s_setprio 0
	s_setprio 1
	v_mfma_f32_16x16x32_bf16 v[64:67], v[178:181], v[24:27], v[96:99]
	v_mfma_f32_16x16x32_bf16 v[24:27], v[202:205], v[24:27], v[32:35]
	v_mfma_f32_16x16x32_bf16 v[116:119], v[228:231], v[28:31], v[24:27]
	v_mfma_f32_16x16x32_bf16 v[24:27], v[178:181], v[60:63], v[36:39]
	v_mfma_f32_16x16x32_bf16 v[96:99], v[198:201], v[100:103], v[24:27]
	v_mfma_f32_16x16x32_bf16 v[24:27], v[202:205], v[60:63], v[40:43]
	v_mfma_f32_16x16x32_bf16 v[100:103], v[228:231], v[100:103], v[24:27]
	v_mfma_f32_16x16x32_bf16 v[24:27], v[178:181], v[232:235], v[44:47]
	v_mfma_f32_16x16x32_bf16 v[80:83], v[198:201], v[236:239], v[24:27]
	v_mfma_f32_16x16x32_bf16 v[24:27], v[202:205], v[232:235], v[48:51]
	v_mfma_f32_16x16x32_bf16 v[84:87], v[228:231], v[236:239], v[24:27]
	v_mfma_f32_16x16x32_bf16 v[24:27], v[178:181], v[240:243], v[52:55]
	v_mfma_f32_16x16x32_bf16 v[112:115], v[198:201], v[28:31], v[64:67]
	v_mfma_f32_16x16x32_bf16 v[64:67], v[198:201], v[244:247], v[24:27]
	v_mfma_f32_16x16x32_bf16 v[24:27], v[202:205], v[240:243], v[56:59]
	v_mfma_f32_16x16x32_bf16 v[68:71], v[228:231], v[244:247], v[24:27]
	s_setprio 0
	s_barrier
	s_mov_b32 m0, s83
	s_nop 3
	v_lshl_add_u64 v[24:25], v[144:145], 0, s[14:15]
	s_add_u32 s52, s64, 0x10080
	ds_read_b128 v[32:35], v151 offset:49152
	ds_read_b128 v[36:39], v151 offset:50176
	ds_read_b128 v[214:217], v151 offset:51200
	ds_read_b128 v[218:221], v151 offset:52224
	ds_read_b128 v[232:235], v151 offset:53248
	ds_read_b128 v[236:239], v151 offset:54272
	ds_read_b128 v[240:243], v151 offset:55296
	ds_read_b128 v[244:247], v151 offset:56320
	global_load_lds_dwordx4 v[24:25], off
	v_lshl_add_u64 v[24:25], v[248:249], 0, s[14:15]
	s_mov_b32 m0, s35
	s_addc_u32 s53, s65, 0
	global_load_lds_dwordx4 v[24:25], off
	v_lshl_add_u64 v[24:25], s[52:53], 0, v[132:133]
	s_mov_b32 m0, s37
	s_nop 0
	global_load_lds_dwordx4 v[24:25], off
	v_lshl_add_u64 v[24:25], s[52:53], 0, v[128:129]
	s_mov_b32 m0, s62
	s_nop 0
	global_load_lds_dwordx4 v[24:25], off
	v_lshl_add_u64 v[24:25], v[250:251], 0, s[14:15]
	s_mov_b32 m0, s70
	s_nop 0
	global_load_lds_dwordx4 v[24:25], off
	v_lshl_add_u64 v[24:25], v[252:253], 0, s[14:15]
	s_mov_b32 m0, s71
	s_nop 0
	global_load_lds_dwordx4 v[24:25], off
	s_waitcnt vmcnt(8)
	s_waitcnt lgkmcnt(0)
	s_barrier
	s_setprio 1
	s_waitcnt lgkmcnt(0)
	v_mfma_f32_16x16x32_bf16 v[24:27], v[8:11], v[32:35], v[140:143]
	v_mfma_f32_16x16x32_bf16 v[60:63], v[12:15], v[36:39], v[24:27]
	v_mfma_f32_16x16x32_bf16 v[24:27], v[16:19], v[32:35], v[154:157]
	v_mfma_f32_16x16x32_bf16 v[56:59], v[20:23], v[36:39], v[24:27]
	v_mfma_f32_16x16x32_bf16 v[24:27], v[8:11], v[214:217], v[158:161]
	v_mfma_f32_16x16x32_bf16 v[44:47], v[12:15], v[218:221], v[24:27]
	v_mfma_f32_16x16x32_bf16 v[24:27], v[16:19], v[214:217], v[162:165]
	v_mfma_f32_16x16x32_bf16 v[40:43], v[20:23], v[218:221], v[24:27]
	v_mfma_f32_16x16x32_bf16 v[24:27], v[8:11], v[232:235], v[166:169]
	v_mfma_f32_16x16x32_bf16 v[0:3], v[8:11], v[240:243], v[0:3]
	v_mfma_f32_16x16x32_bf16 v[28:31], v[12:15], v[236:239], v[24:27]
	v_mfma_f32_16x16x32_bf16 v[24:27], v[16:19], v[232:235], v[170:173]
	v_mfma_f32_16x16x32_bf16 v[12:15], v[12:15], v[244:247], v[0:3]
	v_mfma_f32_16x16x32_bf16 v[0:3], v[16:19], v[240:243], v[4:7]
	v_mfma_f32_16x16x32_bf16 v[24:27], v[20:23], v[236:239], v[24:27]
	v_mfma_f32_16x16x32_bf16 v[8:11], v[20:23], v[244:247], v[0:3]
	s_setprio 0
	s_setprio 1
	v_mfma_f32_16x16x32_bf16 v[0:3], v[178:181], v[32:35], v[206:209]
	v_mfma_f32_16x16x32_bf16 v[48:51], v[198:201], v[36:39], v[0:3]
	v_mfma_f32_16x16x32_bf16 v[0:3], v[202:205], v[32:35], v[210:213]
	v_mfma_f32_16x16x32_bf16 v[52:55], v[228:231], v[36:39], v[0:3]
	v_mfma_f32_16x16x32_bf16 v[0:3], v[178:181], v[214:217], v[222:225]
	v_mfma_f32_16x16x32_bf16 v[32:35], v[198:201], v[218:221], v[0:3]
	v_mfma_f32_16x16x32_bf16 v[0:3], v[202:205], v[214:217], v[182:185]
	v_mfma_f32_16x16x32_bf16 v[36:39], v[228:231], v[218:221], v[0:3]
	v_mfma_f32_16x16x32_bf16 v[0:3], v[178:181], v[232:235], v[186:189]
	v_mfma_f32_16x16x32_bf16 v[16:19], v[198:201], v[236:239], v[0:3]
	v_mfma_f32_16x16x32_bf16 v[0:3], v[202:205], v[232:235], v[190:193]
	v_mfma_f32_16x16x32_bf16 v[20:23], v[228:231], v[236:239], v[0:3]
	v_mfma_f32_16x16x32_bf16 v[0:3], v[178:181], v[240:243], v[194:197]
	v_mfma_f32_16x16x32_bf16 v[4:7], v[198:201], v[244:247], v[0:3]
	v_mfma_f32_16x16x32_bf16 v[0:3], v[202:205], v[240:243], v[174:177]
	v_mfma_f32_16x16x32_bf16 v[0:3], v[228:231], v[244:247], v[0:3]
	s_setprio 0
	s_barrier
	s_andn2_b64 vcc, exec, s[16:17]
	s_cbranch_vccnz .LBB0_1356
	s_barrier

; #define PG8_STAGE(bufoff, gbase, voff) do { _Pragma("unroll") for (int _i = 0; _i < 2; ++_i) \
;         __builtin_amdgcn_global_load_lds((const unsigned*)((const char*)(gbase) + (voff)[_i]), (PG8_LAS unsigned*)(lds + (bufoff) + ldsw + _i * 8192), 16, 0, 0); } while (0)
; #define PG8_LDA(dst, b, h) do { _Pragma("unroll") for (int m = 0; m < 4; ++m) _Pragma("unroll") for (int k = 0; k < 2; ++k) dst[m][k] = *(const PG8_LAS bf16x8*)(lds + PG8_SA(b, h) + aoff + m * 2048 + k * 1024); } while (0)
; #define PG8_MMA(ai, bj, At, Bt) do { __builtin_amdgcn_s_setprio(1); _Pragma("unroll") for (int m = 0; m < 4; ++m) _Pragma("unroll") for (int n = 0; n < 2; ++n) _Pragma("unroll") for (int k = 0; k < 2; ++k) \
;         acc[ai][bj][m][n] = __builtin_amdgcn_mfma_f32_16x16x32_bf16(Bt[n][k], At[m][k], acc[ai][bj][m][n], 0, 0, 0); __builtin_amdgcn_s_setprio(0); } while (0)
; #define PG8_WAIT_V(n) asm volatile("s_waitcnt vmcnt(" #n ")" ::: "memory")
; #define PG8_WAIT_L(n) asm volatile("s_waitcnt lgkmcnt(" #n ")" ::: "memory")
; #define PG8_BAR __builtin_amdgcn_s_barrier()
; #define PG8_SCHED __builtin_amdgcn_sched_barrier(0)
; template <class Epi, class Sched, bool ALIGN_EPI = false, bool SP2 = false>
; __device__ __forceinline__ void gemm_phase(PG8_LAS unsigned char* lds, const Gemm g, const Sched& S, const Epi& E) {
;     ...
;             PG8_WAIT_V(8); PG8_WAIT_L(0); PG8_BAR; PG8_MMA(0, 0, At, B0); PG8_MMA(0, 1, At, B1); PG8_BAR; PG8_SCHED;
;             PG8_LDA(At, 0, 1); PG8_STAGE(PG8_SB(0, 0), b2, voffB); PG8_STAGE(PG8_SB(0, 1), b2 + hstep, voffB); PG8_STAGE(PG8_SA(0, 0), a2, voffA);
.Lrj_P4_0:
	s_waitcnt lgkmcnt(0)
	s_barrier
	s_setprio 1
	s_waitcnt lgkmcnt(0)
	v_mfma_f32_16x16x32_bf16 v[140:143], v[56:59], v[186:189], v[140:143]
	v_mfma_f32_16x16x32_bf16 v[120:123], v[72:75], v[194:197], v[120:123]
	v_mfma_f32_16x16x32_bf16 v[108:111], v[56:59], v[202:205], v[108:111]
	v_mfma_f32_16x16x32_bf16 v[88:91], v[72:75], v[210:213], v[88:91]
	v_mfma_f32_16x16x32_bf16 v[124:127], v[56:59], v[194:197], v[124:127]
	v_mfma_f32_16x16x32_bf16 v[136:139], v[72:75], v[186:189], v[136:139]
	v_mfma_f32_16x16x32_bf16 v[92:95], v[56:59], v[210:213], v[92:95]
	v_mfma_f32_16x16x32_bf16 v[104:107], v[72:75], v[202:205], v[104:107]
	v_mfma_f32_16x16x32_bf16 v[140:143], v[60:63], v[190:193], v[140:143]
	v_mfma_f32_16x16x32_bf16 v[120:123], v[76:79], v[198:201], v[120:123]
	v_mfma_f32_16x16x32_bf16 v[108:111], v[60:63], v[206:209], v[108:111]
	v_mfma_f32_16x16x32_bf16 v[88:91], v[76:79], v[214:217], v[88:91]
	v_mfma_f32_16x16x32_bf16 v[124:127], v[60:63], v[198:201], v[124:127]
	v_mfma_f32_16x16x32_bf16 v[136:139], v[76:79], v[190:193], v[136:139]
	v_mfma_f32_16x16x32_bf16 v[92:95], v[60:63], v[214:217], v[92:95]
	v_mfma_f32_16x16x32_bf16 v[104:107], v[76:79], v[206:209], v[104:107]
	s_setprio 0
	s_setprio 1
	v_mfma_f32_16x16x32_bf16 v[132:135], v[162:165], v[186:189], v[132:135]
	v_mfma_f32_16x16x32_bf16 v[112:115], v[178:181], v[194:197], v[112:115]
	v_mfma_f32_16x16x32_bf16 v[100:103], v[162:165], v[202:205], v[100:103]
	v_mfma_f32_16x16x32_bf16 v[80:83], v[178:181], v[210:213], v[80:83]
	v_mfma_f32_16x16x32_bf16 v[116:119], v[162:165], v[194:197], v[116:119]
	v_mfma_f32_16x16x32_bf16 v[128:131], v[178:181], v[186:189], v[128:131]
	v_mfma_f32_16x16x32_bf16 v[84:87], v[162:165], v[210:213], v[84:87]
	v_mfma_f32_16x16x32_bf16 v[96:99], v[178:181], v[202:205], v[96:99]
	v_mfma_f32_16x16x32_bf16 v[132:135], v[166:169], v[190:193], v[132:135]
	v_mfma_f32_16x16x32_bf16 v[112:115], v[182:185], v[198:201], v[112:115]
	v_mfma_f32_16x16x32_bf16 v[100:103], v[166:169], v[206:209], v[100:103]
	v_mfma_f32_16x16x32_bf16 v[80:83], v[182:185], v[214:217], v[80:83]
	v_mfma_f32_16x16x32_bf16 v[116:119], v[166:169], v[198:201], v[116:119]
	v_mfma_f32_16x16x32_bf16 v[128:131], v[182:185], v[190:193], v[128:131]
	v_mfma_f32_16x16x32_bf16 v[84:87], v[166:169], v[214:217], v[84:87]
	v_mfma_f32_16x16x32_bf16 v[96:99], v[182:185], v[206:209], v[96:99]
	s_setprio 0
	s_barrier
	s_add_i32 s76, s64, s41
	v_lshl_add_u64 v[218:219], s[36:37], 0, v[146:147]
	s_mov_b32 m0, s76
	ds_read_b128 v[186:189], v175 offset:16384
	ds_read_b128 v[190:193], v175 offset:17408
	ds_read_b128 v[194:197], v175 offset:18432
	ds_read_b128 v[198:201], v175 offset:19456
	ds_read_b128 v[202:205], v175 offset:20480
	ds_read_b128 v[206:209], v175 offset:21504
	ds_read_b128 v[210:213], v175 offset:22528
	ds_read_b128 v[214:217], v175 offset:23552
	global_load_lds_dwordx4 v[218:219], off
	s_add_i32 m0, s76, 0x2000
	s_add_u32 s76, s36, 0x40000
	v_lshl_add_u64 v[220:221], s[36:37], 0, v[150:151]
	s_addc_u32 s77, s37, 0
	s_add_i32 s80, s65, s41
	global_load_lds_dwordx4 v[220:221], off
	v_lshl_add_u64 v[222:223], s[76:77], 0, v[146:147]
	s_mov_b32 m0, s80
	v_lshl_add_u64 v[224:225], s[38:39], 0, v[148:149]
	global_load_lds_dwordx4 v[222:223], off
	v_lshl_add_u64 v[222:223], s[76:77], 0, v[150:151]
	s_add_i32 m0, s80, 0x2000
	s_nop 0
	global_load_lds_dwordx4 v[222:223], off
	v_lshl_add_u64 v[222:223], s[38:39], 0, v[144:145]
	s_mov_b32 m0, s42
	s_nop 0
	global_load_lds_dwordx4 v[222:223], off
	s_mov_b32 m0, s43
	s_nop 0
	global_load_lds_dwordx4 v[224:225], off
	s_cmp_eq_u32 s99, 1
	s_cbranch_scc1 .Lrw_P4_1
	s_waitcnt vmcnt(8)
	s_branch .Lrj_P4_1

; #define PG8_STAGE(bufoff, gbase, voff) do { _Pragma("unroll") for (int _i = 0; _i < 2; ++_i) \
;         __builtin_amdgcn_global_load_lds((const unsigned*)((const char*)(gbase) + (voff)[_i]), (PG8_LAS unsigned*)(lds + (bufoff) + ldsw + _i * 8192), 16, 0, 0); } while (0)
; #define PG8_LDA(dst, b, h) do { _Pragma("unroll") for (int m = 0; m < 4; ++m) _Pragma("unroll") for (int k = 0; k < 2; ++k) dst[m][k] = *(const PG8_LAS bf16x8*)(lds + PG8_SA(b, h) + aoff + m * 2048 + k * 1024); } while (0)
; #define PG8_LDB(dst, b, h) do { _Pragma("unroll") for (int n = 0; n < 2; ++n) _Pragma("unroll") for (int k = 0; k < 2; ++k) dst[n][k] = *(const PG8_LAS bf16x8*)(lds + PG8_SB(b, h) + boff + n * 2048 + k * 1024); } while (0)
; #define PG8_MMA(ai, bj, At, Bt) do { __builtin_amdgcn_s_setprio(1); _Pragma("unroll") for (int m = 0; m < 4; ++m) _Pragma("unroll") for (int n = 0; n < 2; ++n) _Pragma("unroll") for (int k = 0; k < 2; ++k) \
;         acc[ai][bj][m][n] = __builtin_amdgcn_mfma_f32_16x16x32_bf16(Bt[n][k], At[m][k], acc[ai][bj][m][n], 0, 0, 0); __builtin_amdgcn_s_setprio(0); } while (0)
; #define PG8_WAIT_V(n) asm volatile("s_waitcnt vmcnt(" #n ")" ::: "memory")
; #define PG8_WAIT_L(n) asm volatile("s_waitcnt lgkmcnt(" #n ")" ::: "memory")
; #define PG8_BAR __builtin_amdgcn_s_barrier()
; #define PG8_SCHED __builtin_amdgcn_sched_barrier(0)
; template <class Epi, class Sched, bool ALIGN_EPI = false, bool SP2 = false>
; __device__ __forceinline__ void gemm_phase(PG8_LAS unsigned char* lds, const Gemm g, const Sched& S, const Epi& E) {
;     ...
;             PG8_WAIT_V(8); PG8_WAIT_L(0); PG8_BAR; PG8_MMA(1, 0, At, B0); PG8_MMA(1, 1, At, B1); PG8_BAR; PG8_SCHED;
;             PG8_LDB(B0, 1, 0); PG8_LDB(B1, 1, 1); PG8_SCHED; PG8_LDA(At, 1, 0); PG8_STAGE(PG8_SA(0, 1), a2 + hstep, voffA);
;             PG8_WAIT_V(8); PG8_WAIT_L(0); PG8_BAR; PG8_MMA(0, 0, At, B0); PG8_MMA(0, 1, At, B1); PG8_BAR; PG8_SCHED;
.Lrj_P4_1:
	s_waitcnt lgkmcnt(0)
	s_barrier
	s_setprio 1
	s_waitcnt lgkmcnt(0)
	v_mfma_f32_16x16x32_bf16 v[68:71], v[56:59], v[186:189], v[68:71]
	v_mfma_f32_16x16x32_bf16 v[40:43], v[72:75], v[194:197], v[40:43]
	v_mfma_f32_16x16x32_bf16 v[28:31], v[56:59], v[202:205], v[28:31]
	v_mfma_f32_16x16x32_bf16 v[8:11], v[72:75], v[210:213], v[8:11]
	v_mfma_f32_16x16x32_bf16 v[44:47], v[56:59], v[194:197], v[44:47]
	v_mfma_f32_16x16x32_bf16 v[64:67], v[72:75], v[186:189], v[64:67]
	v_mfma_f32_16x16x32_bf16 v[12:15], v[56:59], v[210:213], v[12:15]
	v_mfma_f32_16x16x32_bf16 v[24:27], v[72:75], v[202:205], v[24:27]
	v_mfma_f32_16x16x32_bf16 v[68:71], v[60:63], v[190:193], v[68:71]
	v_mfma_f32_16x16x32_bf16 v[40:43], v[76:79], v[198:201], v[40:43]
	v_mfma_f32_16x16x32_bf16 v[28:31], v[60:63], v[206:209], v[28:31]
	v_mfma_f32_16x16x32_bf16 v[8:11], v[76:79], v[214:217], v[8:11]
	v_mfma_f32_16x16x32_bf16 v[44:47], v[60:63], v[198:201], v[44:47]
	v_mfma_f32_16x16x32_bf16 v[64:67], v[76:79], v[190:193], v[64:67]
	v_mfma_f32_16x16x32_bf16 v[12:15], v[60:63], v[214:217], v[12:15]
	v_mfma_f32_16x16x32_bf16 v[24:27], v[76:79], v[206:209], v[24:27]
	s_setprio 0
	s_setprio 1
	v_mfma_f32_16x16x32_bf16 v[52:55], v[162:165], v[186:189], v[52:55]
	v_mfma_f32_16x16x32_bf16 v[32:35], v[178:181], v[194:197], v[32:35]
	v_mfma_f32_16x16x32_bf16 v[20:23], v[162:165], v[202:205], v[20:23]
	v_mfma_f32_16x16x32_bf16 v[0:3], v[178:181], v[210:213], v[0:3]
	v_mfma_f32_16x16x32_bf16 v[36:39], v[162:165], v[194:197], v[36:39]
	v_mfma_f32_16x16x32_bf16 v[48:51], v[178:181], v[186:189], v[48:51]
	v_mfma_f32_16x16x32_bf16 v[4:7], v[162:165], v[210:213], v[4:7]
	v_mfma_f32_16x16x32_bf16 v[16:19], v[178:181], v[202:205], v[16:19]
	v_mfma_f32_16x16x32_bf16 v[52:55], v[166:169], v[190:193], v[52:55]
	v_mfma_f32_16x16x32_bf16 v[32:35], v[182:185], v[198:201], v[32:35]
	v_mfma_f32_16x16x32_bf16 v[20:23], v[166:169], v[206:209], v[20:23]
	v_mfma_f32_16x16x32_bf16 v[0:3], v[182:185], v[214:217], v[0:3]
	v_mfma_f32_16x16x32_bf16 v[36:39], v[166:169], v[198:201], v[36:39]
	v_mfma_f32_16x16x32_bf16 v[48:51], v[182:185], v[190:193], v[48:51]
	v_mfma_f32_16x16x32_bf16 v[4:7], v[166:169], v[214:217], v[4:7]
	v_mfma_f32_16x16x32_bf16 v[16:19], v[182:185], v[206:209], v[16:19]
	s_setprio 0
	s_barrier
	s_add_i32 s76, 0, 0x18000
	s_add_i32 s77, 0, 0x1c000
	v_add_u32_e32 v76, s76, v171
	v_add_u32_e32 v152, s77, v171
	ds_read_b128 v[56:59], v76
	ds_read_b128 v[60:63], v76 offset:1024
	ds_read_b128 v[72:75], v76 offset:2048
	ds_read_b128 v[76:79], v76 offset:3072
	ds_read_b128 v[162:165], v152
	ds_read_b128 v[166:169], v152 offset:1024
	ds_read_b128 v[178:181], v152 offset:2048
	ds_read_b128 v[182:185], v152 offset:3072
	s_add_u32 s38, s38, 0x40000
	s_addc_u32 s39, s39, 0
	s_mov_b32 m0, s46
	v_lshl_add_u64 v[228:229], s[38:39], 0, v[144:145]
	ds_read_b128 v[186:189], v175 offset:32768
	ds_read_b128 v[190:193], v175 offset:33792
	ds_read_b128 v[194:197], v175 offset:34816
	ds_read_b128 v[198:201], v175 offset:35840
	ds_read_b128 v[202:205], v175 offset:36864
	ds_read_b128 v[206:209], v175 offset:37888
	ds_read_b128 v[210:213], v175 offset:38912
	ds_read_b128 v[214:217], v175 offset:39936
	global_load_lds_dwordx4 v[228:229], off
	v_lshl_add_u64 v[228:229], s[38:39], 0, v[148:149]
	s_mov_b32 m0, s47
	s_nop 0
	global_load_lds_dwordx4 v[228:229], off
	s_waitcnt vmcnt(8)
	s_waitcnt lgkmcnt(0)
	s_barrier
	s_setprio 1
	s_waitcnt lgkmcnt(0)
	v_mfma_f32_16x16x32_bf16 v[140:143], v[56:59], v[186:189], v[140:143]
	v_mfma_f32_16x16x32_bf16 v[120:123], v[72:75], v[194:197], v[120:123]
	v_mfma_f32_16x16x32_bf16 v[108:111], v[56:59], v[202:205], v[108:111]
	v_mfma_f32_16x16x32_bf16 v[88:91], v[72:75], v[210:213], v[88:91]
	v_mfma_f32_16x16x32_bf16 v[124:127], v[56:59], v[194:197], v[124:127]
	v_mfma_f32_16x16x32_bf16 v[136:139], v[72:75], v[186:189], v[136:139]
	v_mfma_f32_16x16x32_bf16 v[92:95], v[56:59], v[210:213], v[92:95]
	v_mfma_f32_16x16x32_bf16 v[104:107], v[72:75], v[202:205], v[104:107]
	v_mfma_f32_16x16x32_bf16 v[140:143], v[60:63], v[190:193], v[140:143]
	v_mfma_f32_16x16x32_bf16 v[120:123], v[76:79], v[198:201], v[120:123]
	v_mfma_f32_16x16x32_bf16 v[108:111], v[60:63], v[206:209], v[108:111]
	v_mfma_f32_16x16x32_bf16 v[88:91], v[76:79], v[214:217], v[88:91]
	v_mfma_f32_16x16x32_bf16 v[124:127], v[60:63], v[198:201], v[124:127]
	v_mfma_f32_16x16x32_bf16 v[136:139], v[76:79], v[190:193], v[136:139]
	v_mfma_f32_16x16x32_bf16 v[92:95], v[60:63], v[214:217], v[92:95]
	v_mfma_f32_16x16x32_bf16 v[104:107], v[76:79], v[206:209], v[104:107]
	s_setprio 0
	s_setprio 1
	v_mfma_f32_16x16x32_bf16 v[132:135], v[162:165], v[186:189], v[132:135]
	v_mfma_f32_16x16x32_bf16 v[112:115], v[178:181], v[194:197], v[112:115]
	v_mfma_f32_16x16x32_bf16 v[100:103], v[162:165], v[202:205], v[100:103]
	v_mfma_f32_16x16x32_bf16 v[80:83], v[178:181], v[210:213], v[80:83]
	v_mfma_f32_16x16x32_bf16 v[116:119], v[162:165], v[194:197], v[116:119]
	v_mfma_f32_16x16x32_bf16 v[128:131], v[178:181], v[186:189], v[128:131]
	v_mfma_f32_16x16x32_bf16 v[84:87], v[162:165], v[210:213], v[84:87]
	v_mfma_f32_16x16x32_bf16 v[96:99], v[178:181], v[202:205], v[96:99]
	v_mfma_f32_16x16x32_bf16 v[132:135], v[166:169], v[190:193], v[132:135]
	v_mfma_f32_16x16x32_bf16 v[112:115], v[182:185], v[198:201], v[112:115]
	v_mfma_f32_16x16x32_bf16 v[100:103], v[166:169], v[206:209], v[100:103]
	v_mfma_f32_16x16x32_bf16 v[80:83], v[182:185], v[214:217], v[80:83]
	v_mfma_f32_16x16x32_bf16 v[116:119], v[166:169], v[198:201], v[116:119]
	v_mfma_f32_16x16x32_bf16 v[128:131], v[182:185], v[190:193], v[128:131]
	v_mfma_f32_16x16x32_bf16 v[84:87], v[166:169], v[214:217], v[84:87]
	v_mfma_f32_16x16x32_bf16 v[96:99], v[182:185], v[206:209], v[96:99]
	s_setprio 0
	s_barrier
; #define PG8_STAGE(bufoff, gbase, voff) do { _Pragma("unroll") for (int _i = 0; _i < 2; ++_i) \
;         __builtin_amdgcn_global_load_lds((const unsigned*)((const char*)(gbase) + (voff)[_i]), (PG8_LAS unsigned*)(lds + (bufoff) + ldsw + _i * 8192), 16, 0, 0); } while (0)
; #define PG8_LDA(dst, b, h) do { _Pragma("unroll") for (int m = 0; m < 4; ++m) _Pragma("unroll") for (int k = 0; k < 2; ++k) dst[m][k] = *(const PG8_LAS bf16x8*)(lds + PG8_SA(b, h) + aoff + m * 2048 + k * 1024); } while (0)
; #define PG8_MMA(ai, bj, At, Bt) do { __builtin_amdgcn_s_setprio(1); _Pragma("unroll") for (int m = 0; m < 4; ++m) _Pragma("unroll") for (int n = 0; n < 2; ++n) _Pragma("unroll") for (int k = 0; k < 2; ++k) \
;         acc[ai][bj][m][n] = __builtin_amdgcn_mfma_f32_16x16x32_bf16(Bt[n][k], At[m][k], acc[ai][bj][m][n], 0, 0, 0); __builtin_amdgcn_s_setprio(0); } while (0)
; #define PG8_WAIT_V(n) asm volatile("s_waitcnt vmcnt(" #n ")" ::: "memory")
; #define PG8_WAIT_L(n) asm volatile("s_waitcnt lgkmcnt(" #n ")" ::: "memory")
; #define PG8_BAR __builtin_amdgcn_s_barrier()
; #define PG8_SCHED __builtin_amdgcn_sched_barrier(0)
; template <class Epi, class Sched, bool ALIGN_EPI = false, bool SP2 = false>
; __device__ __forceinline__ void gemm_phase(PG8_LAS unsigned char* lds, const Gemm g, const Sched& S, const Epi& E) {
;     ...
;             PG8_LDA(At, 1, 1); PG8_STAGE(PG8_SB(1, 0), b3, voffB); PG8_STAGE(PG8_SB(1, 1), b3 + hstep, voffB); PG8_STAGE(PG8_SA(1, 0), a3, voffA);
;             PG8_WAIT_V(8); PG8_WAIT_L(0); PG8_BAR; PG8_MMA(1, 0, At, B0); PG8_MMA(1, 1, At, B1); PG8_BAR; PG8_SCHED;
;     ...
;         if constexpr (ALIGN_EPI) { if (wr == 0) PG8_BAR; }
	s_add_i32 s38, s76, s41
	v_lshl_add_u64 v[218:219], v[218:219], 0, s[18:19]
	s_mov_b32 m0, s38
	ds_read_b128 v[186:189], v175 offset:49152
	ds_read_b128 v[190:193], v175 offset:50176
	ds_read_b128 v[194:197], v175 offset:51200
	ds_read_b128 v[198:201], v175 offset:52224
	ds_read_b128 v[202:205], v175 offset:53248
	ds_read_b128 v[206:209], v175 offset:54272
	ds_read_b128 v[210:213], v175 offset:55296
	ds_read_b128 v[214:217], v175 offset:56320
	global_load_lds_dwordx4 v[218:219], off
	s_add_i32 m0, s38, 0x2000
	s_add_u32 s36, s36, 0x40080
	v_lshl_add_u64 v[218:219], v[220:221], 0, s[18:19]
	s_addc_u32 s37, s37, 0
	s_add_i32 s38, s77, s41
	global_load_lds_dwordx4 v[218:219], off
	v_lshl_add_u64 v[218:219], s[36:37], 0, v[146:147]
	s_mov_b32 m0, s38
	s_nop 0
	global_load_lds_dwordx4 v[218:219], off
	v_lshl_add_u64 v[218:219], s[36:37], 0, v[150:151]
	s_add_i32 m0, s38, 0x2000
	s_nop 0
	global_load_lds_dwordx4 v[218:219], off
	v_lshl_add_u64 v[218:219], v[222:223], 0, s[18:19]
	s_mov_b32 m0, s53
	s_nop 0
	global_load_lds_dwordx4 v[218:219], off
	v_lshl_add_u64 v[218:219], v[224:225], 0, s[18:19]
	s_mov_b32 m0, s60
	s_nop 0
	global_load_lds_dwordx4 v[218:219], off
	s_waitcnt vmcnt(8)
	s_waitcnt lgkmcnt(0)
	s_barrier
	s_setprio 1
	s_waitcnt lgkmcnt(0)
	v_mfma_f32_16x16x32_bf16 v[68:71], v[56:59], v[186:189], v[68:71]
	v_mfma_f32_16x16x32_bf16 v[40:43], v[72:75], v[194:197], v[40:43]
	v_mfma_f32_16x16x32_bf16 v[28:31], v[56:59], v[202:205], v[28:31]
	v_mfma_f32_16x16x32_bf16 v[8:11], v[72:75], v[210:213], v[8:11]
	v_mfma_f32_16x16x32_bf16 v[44:47], v[56:59], v[194:197], v[44:47]
	v_mfma_f32_16x16x32_bf16 v[64:67], v[72:75], v[186:189], v[64:67]
	v_mfma_f32_16x16x32_bf16 v[12:15], v[56:59], v[210:213], v[12:15]
	v_mfma_f32_16x16x32_bf16 v[24:27], v[72:75], v[202:205], v[24:27]
	v_mfma_f32_16x16x32_bf16 v[68:71], v[60:63], v[190:193], v[68:71]
	v_mfma_f32_16x16x32_bf16 v[40:43], v[76:79], v[198:201], v[40:43]
	v_mfma_f32_16x16x32_bf16 v[28:31], v[60:63], v[206:209], v[28:31]
	v_mfma_f32_16x16x32_bf16 v[8:11], v[76:79], v[214:217], v[8:11]
	v_mfma_f32_16x16x32_bf16 v[44:47], v[60:63], v[198:201], v[44:47]
	v_mfma_f32_16x16x32_bf16 v[64:67], v[76:79], v[190:193], v[64:67]
	v_mfma_f32_16x16x32_bf16 v[12:15], v[60:63], v[214:217], v[12:15]
	v_mfma_f32_16x16x32_bf16 v[24:27], v[76:79], v[206:209], v[24:27]
	s_setprio 0
	s_setprio 1
	v_mfma_f32_16x16x32_bf16 v[52:55], v[162:165], v[186:189], v[52:55]
	v_mfma_f32_16x16x32_bf16 v[32:35], v[178:181], v[194:197], v[32:35]
	v_mfma_f32_16x16x32_bf16 v[20:23], v[162:165], v[202:205], v[20:23]
	v_mfma_f32_16x16x32_bf16 v[0:3], v[178:181], v[210:213], v[0:3]
	v_mfma_f32_16x16x32_bf16 v[36:39], v[162:165], v[194:197], v[36:39]
	v_mfma_f32_16x16x32_bf16 v[48:51], v[178:181], v[186:189], v[48:51]
	v_mfma_f32_16x16x32_bf16 v[4:7], v[162:165], v[210:213], v[4:7]
	v_mfma_f32_16x16x32_bf16 v[16:19], v[178:181], v[202:205], v[16:19]
	v_mfma_f32_16x16x32_bf16 v[52:55], v[166:169], v[190:193], v[52:55]
	v_mfma_f32_16x16x32_bf16 v[32:35], v[182:185], v[198:201], v[32:35]
	v_mfma_f32_16x16x32_bf16 v[20:23], v[166:169], v[206:209], v[20:23]
	v_mfma_f32_16x16x32_bf16 v[0:3], v[182:185], v[214:217], v[0:3]
	v_mfma_f32_16x16x32_bf16 v[36:39], v[166:169], v[198:201], v[36:39]
	v_mfma_f32_16x16x32_bf16 v[48:51], v[182:185], v[190:193], v[48:51]
	v_mfma_f32_16x16x32_bf16 v[4:7], v[166:169], v[214:217], v[4:7]
	v_mfma_f32_16x16x32_bf16 v[16:19], v[182:185], v[206:209], v[16:19]
	s_setprio 0
	s_barrier
	s_mov_b32 s99, 0
	s_add_i32 s75, s75, 2
	s_add_u32 s34, s34, 0x100
	s_addc_u32 s35, s35, 0
	s_add_u32 s73, s73, 0x100
	s_addc_u32 s74, s74, 0
	s_cmp_gt_u32 s75, 13
	s_cbranch_scc0 .LBB0_1423
	s_and_b64 vcc, exec, s[20:21]
	s_cbranch_vccz .LBB0_1426
	s_barrier

; #define PG8_STAGE(bufoff, gbase, voff) do { _Pragma("unroll") for (int _i = 0; _i < 2; ++_i) \
;         __builtin_amdgcn_global_load_lds((const unsigned*)((const char*)(gbase) + (voff)[_i]), (PG8_LAS unsigned*)(lds + (bufoff) + ldsw + _i * 8192), 16, 0, 0); } while (0)
; #define PG8_LDA(dst, b, h) do { _Pragma("unroll") for (int m = 0; m < 4; ++m) _Pragma("unroll") for (int k = 0; k < 2; ++k) dst[m][k] = *(const PG8_LAS bf16x8*)(lds + PG8_SA(b, h) + aoff + m * 2048 + k * 1024); } while (0)
; #define PG8_MMA(ai, bj, At, Bt) do { __builtin_amdgcn_s_setprio(1); _Pragma("unroll") for (int m = 0; m < 4; ++m) _Pragma("unroll") for (int n = 0; n < 2; ++n) _Pragma("unroll") for (int k = 0; k < 2; ++k) \
;         acc[ai][bj][m][n] = __builtin_amdgcn_mfma_f32_16x16x32_bf16(Bt[n][k], At[m][k], acc[ai][bj][m][n], 0, 0, 0); __builtin_amdgcn_s_setprio(0); } while (0)
; #define PG8_WAIT_V(n) asm volatile("s_waitcnt vmcnt(" #n ")" ::: "memory")
; #define PG8_WAIT_L(n) asm volatile("s_waitcnt lgkmcnt(" #n ")" ::: "memory")
; #define PG8_BAR __builtin_amdgcn_s_barrier()
; #define PG8_SCHED __builtin_amdgcn_sched_barrier(0)
; template <class Epi, class Sched, bool ALIGN_EPI = false, bool SP2 = false>
; __device__ __forceinline__ void gemm_phase(PG8_LAS unsigned char* lds, const Gemm g, const Sched& S, const Epi& E) {
;     ...
;             PG8_WAIT_V(8); PG8_WAIT_L(0); PG8_BAR; PG8_MMA(0, 0, At, B0); PG8_MMA(0, 1, At, B1); PG8_BAR; PG8_SCHED;
;             PG8_LDA(At, 0, 1); PG8_STAGE(PG8_SB(0, 0), b2, voffB); PG8_STAGE(PG8_SB(0, 1), b2 + hstep, voffB); PG8_STAGE(PG8_SA(0, 0), a2, voffA);
.Lrj_P5_0:
	s_waitcnt lgkmcnt(0)
	s_barrier
	s_setprio 1
	s_waitcnt lgkmcnt(0)
	v_mfma_f32_16x16x32_bf16 v[124:127], v[144:147], v[184:187], v[124:127]
	v_mfma_f32_16x16x32_bf16 v[104:107], v[160:163], v[192:195], v[104:107]
	v_mfma_f32_16x16x32_bf16 v[92:95], v[144:147], v[200:203], v[92:95]
	v_mfma_f32_16x16x32_bf16 v[72:75], v[160:163], v[208:211], v[72:75]
	v_mfma_f32_16x16x32_bf16 v[108:111], v[144:147], v[192:195], v[108:111]
	v_mfma_f32_16x16x32_bf16 v[120:123], v[160:163], v[184:187], v[120:123]
	v_mfma_f32_16x16x32_bf16 v[76:79], v[144:147], v[208:211], v[76:79]
	v_mfma_f32_16x16x32_bf16 v[88:91], v[160:163], v[200:203], v[88:91]
	v_mfma_f32_16x16x32_bf16 v[124:127], v[156:159], v[188:191], v[124:127]
	v_mfma_f32_16x16x32_bf16 v[104:107], v[164:167], v[196:199], v[104:107]
	v_mfma_f32_16x16x32_bf16 v[92:95], v[156:159], v[204:207], v[92:95]
	v_mfma_f32_16x16x32_bf16 v[72:75], v[164:167], v[212:215], v[72:75]
	v_mfma_f32_16x16x32_bf16 v[108:111], v[156:159], v[196:199], v[108:111]
	v_mfma_f32_16x16x32_bf16 v[120:123], v[164:167], v[188:191], v[120:123]
	v_mfma_f32_16x16x32_bf16 v[76:79], v[156:159], v[212:215], v[76:79]
	v_mfma_f32_16x16x32_bf16 v[88:91], v[164:167], v[204:207], v[88:91]
	s_setprio 0
	s_setprio 1
	v_mfma_f32_16x16x32_bf16 v[116:119], v[168:171], v[184:187], v[116:119]
	v_mfma_f32_16x16x32_bf16 v[96:99], v[176:179], v[192:195], v[96:99]
	v_mfma_f32_16x16x32_bf16 v[84:87], v[168:171], v[200:203], v[84:87]
	v_mfma_f32_16x16x32_bf16 v[64:67], v[176:179], v[208:211], v[64:67]
	v_mfma_f32_16x16x32_bf16 v[100:103], v[168:171], v[192:195], v[100:103]
	v_mfma_f32_16x16x32_bf16 v[112:115], v[176:179], v[184:187], v[112:115]
	v_mfma_f32_16x16x32_bf16 v[68:71], v[168:171], v[208:211], v[68:71]
	v_mfma_f32_16x16x32_bf16 v[80:83], v[176:179], v[200:203], v[80:83]
	v_mfma_f32_16x16x32_bf16 v[116:119], v[172:175], v[188:191], v[116:119]
	v_mfma_f32_16x16x32_bf16 v[96:99], v[180:183], v[196:199], v[96:99]
	v_mfma_f32_16x16x32_bf16 v[84:87], v[172:175], v[204:207], v[84:87]
	v_mfma_f32_16x16x32_bf16 v[64:67], v[180:183], v[212:215], v[64:67]
	v_mfma_f32_16x16x32_bf16 v[100:103], v[172:175], v[196:199], v[100:103]
	v_mfma_f32_16x16x32_bf16 v[112:115], v[180:183], v[188:191], v[112:115]
	v_mfma_f32_16x16x32_bf16 v[68:71], v[172:175], v[212:215], v[68:71]
	v_mfma_f32_16x16x32_bf16 v[80:83], v[180:183], v[204:207], v[80:83]
	s_setprio 0
	s_barrier
	s_add_i32 s66, s52, s39
	v_lshl_add_u64 v[216:217], s[34:35], 0, v[132:133]
	s_mov_b32 m0, s66
	ds_read_b128 v[184:187], v153 offset:16384
	ds_read_b128 v[188:191], v153 offset:17408
	ds_read_b128 v[192:195], v153 offset:18432
	ds_read_b128 v[196:199], v153 offset:19456
	ds_read_b128 v[200:203], v153 offset:20480
	ds_read_b128 v[204:207], v153 offset:21504
	ds_read_b128 v[208:211], v153 offset:22528
	ds_read_b128 v[212:215], v153 offset:23552
	global_load_lds_dwordx4 v[216:217], off
	s_add_i32 m0, s66, 0x2000
	s_add_u32 s66, s34, 0x40000
	v_lshl_add_u64 v[218:219], s[34:35], 0, v[128:129]
	s_addc_u32 s67, s35, 0
	s_add_i32 s68, s53, s39
	global_load_lds_dwordx4 v[218:219], off
	v_lshl_add_u64 v[220:221], s[66:67], 0, v[132:133]
	s_mov_b32 m0, s68
	v_lshl_add_u64 v[222:223], s[36:37], 0, v[130:131]
	global_load_lds_dwordx4 v[220:221], off
	v_lshl_add_u64 v[220:221], s[66:67], 0, v[128:129]
	s_add_i32 m0, s68, 0x2000
	s_nop 0
	global_load_lds_dwordx4 v[220:221], off
	v_lshl_add_u64 v[220:221], s[36:37], 0, v[134:135]
	s_mov_b32 m0, s29
	s_nop 0
	global_load_lds_dwordx4 v[220:221], off
	s_mov_b32 m0, s42
	s_nop 0
	global_load_lds_dwordx4 v[222:223], off
	s_cmp_eq_u32 s99, 1
	s_cbranch_scc1 .Lrw_P5_1
	s_waitcnt vmcnt(8)
	s_branch .Lrj_P5_1

; #define PG8_STAGE(bufoff, gbase, voff) do { _Pragma("unroll") for (int _i = 0; _i < 2; ++_i) \
;         __builtin_amdgcn_global_load_lds((const unsigned*)((const char*)(gbase) + (voff)[_i]), (PG8_LAS unsigned*)(lds + (bufoff) + ldsw + _i * 8192), 16, 0, 0); } while (0)
; #define PG8_LDA(dst, b, h) do { _Pragma("unroll") for (int m = 0; m < 4; ++m) _Pragma("unroll") for (int k = 0; k < 2; ++k) dst[m][k] = *(const PG8_LAS bf16x8*)(lds + PG8_SA(b, h) + aoff + m * 2048 + k * 1024); } while (0)
; #define PG8_LDB(dst, b, h) do { _Pragma("unroll") for (int n = 0; n < 2; ++n) _Pragma("unroll") for (int k = 0; k < 2; ++k) dst[n][k] = *(const PG8_LAS bf16x8*)(lds + PG8_SB(b, h) + boff + n * 2048 + k * 1024); } while (0)
; #define PG8_MMA(ai, bj, At, Bt) do { __builtin_amdgcn_s_setprio(1); _Pragma("unroll") for (int m = 0; m < 4; ++m) _Pragma("unroll") for (int n = 0; n < 2; ++n) _Pragma("unroll") for (int k = 0; k < 2; ++k) \
;         acc[ai][bj][m][n] = __builtin_amdgcn_mfma_f32_16x16x32_bf16(Bt[n][k], At[m][k], acc[ai][bj][m][n], 0, 0, 0); __builtin_amdgcn_s_setprio(0); } while (0)
; #define PG8_WAIT_V(n) asm volatile("s_waitcnt vmcnt(" #n ")" ::: "memory")
; #define PG8_WAIT_L(n) asm volatile("s_waitcnt lgkmcnt(" #n ")" ::: "memory")
; #define PG8_BAR __builtin_amdgcn_s_barrier()
; #define PG8_SCHED __builtin_amdgcn_sched_barrier(0)
; template <class Epi, class Sched, bool ALIGN_EPI = false, bool SP2 = false>
; __device__ __forceinline__ void gemm_phase(PG8_LAS unsigned char* lds, const Gemm g, const Sched& S, const Epi& E) {
;     ...
;             PG8_WAIT_V(8); PG8_WAIT_L(0); PG8_BAR; PG8_MMA(1, 0, At, B0); PG8_MMA(1, 1, At, B1); PG8_BAR; PG8_SCHED;
;             PG8_LDB(B0, 1, 0); PG8_LDB(B1, 1, 1); PG8_SCHED; PG8_LDA(At, 1, 0); PG8_STAGE(PG8_SA(0, 1), a2 + hstep, voffA);
;             PG8_WAIT_V(8); PG8_WAIT_L(0); PG8_BAR; PG8_MMA(0, 0, At, B0); PG8_MMA(0, 1, At, B1); PG8_BAR; PG8_SCHED;
.Lrj_P5_1:
	s_waitcnt lgkmcnt(0)
	s_barrier
	s_setprio 1
	s_waitcnt lgkmcnt(0)
	v_mfma_f32_16x16x32_bf16 v[60:63], v[144:147], v[184:187], v[60:63]
	v_mfma_f32_16x16x32_bf16 v[40:43], v[160:163], v[192:195], v[40:43]
	v_mfma_f32_16x16x32_bf16 v[28:31], v[144:147], v[200:203], v[28:31]
	v_mfma_f32_16x16x32_bf16 v[8:11], v[160:163], v[208:211], v[8:11]
	v_mfma_f32_16x16x32_bf16 v[44:47], v[144:147], v[192:195], v[44:47]
	v_mfma_f32_16x16x32_bf16 v[56:59], v[160:163], v[184:187], v[56:59]
	v_mfma_f32_16x16x32_bf16 v[12:15], v[144:147], v[208:211], v[12:15]
	v_mfma_f32_16x16x32_bf16 v[24:27], v[160:163], v[200:203], v[24:27]
	v_mfma_f32_16x16x32_bf16 v[60:63], v[156:159], v[188:191], v[60:63]
	v_mfma_f32_16x16x32_bf16 v[40:43], v[164:167], v[196:199], v[40:43]
	v_mfma_f32_16x16x32_bf16 v[28:31], v[156:159], v[204:207], v[28:31]
	v_mfma_f32_16x16x32_bf16 v[8:11], v[164:167], v[212:215], v[8:11]
	v_mfma_f32_16x16x32_bf16 v[44:47], v[156:159], v[196:199], v[44:47]
	v_mfma_f32_16x16x32_bf16 v[56:59], v[164:167], v[188:191], v[56:59]
	v_mfma_f32_16x16x32_bf16 v[12:15], v[156:159], v[212:215], v[12:15]
	v_mfma_f32_16x16x32_bf16 v[24:27], v[164:167], v[204:207], v[24:27]
	s_setprio 0
	s_setprio 1
	v_mfma_f32_16x16x32_bf16 v[52:55], v[168:171], v[184:187], v[52:55]
	v_mfma_f32_16x16x32_bf16 v[32:35], v[176:179], v[192:195], v[32:35]
	v_mfma_f32_16x16x32_bf16 v[20:23], v[168:171], v[200:203], v[20:23]
	v_mfma_f32_16x16x32_bf16 v[0:3], v[176:179], v[208:211], v[0:3]
	v_mfma_f32_16x16x32_bf16 v[36:39], v[168:171], v[192:195], v[36:39]
	v_mfma_f32_16x16x32_bf16 v[48:51], v[176:179], v[184:187], v[48:51]
	v_mfma_f32_16x16x32_bf16 v[4:7], v[168:171], v[208:211], v[4:7]
	v_mfma_f32_16x16x32_bf16 v[16:19], v[176:179], v[200:203], v[16:19]
	v_mfma_f32_16x16x32_bf16 v[52:55], v[172:175], v[188:191], v[52:55]
	v_mfma_f32_16x16x32_bf16 v[32:35], v[180:183], v[196:199], v[32:35]
	v_mfma_f32_16x16x32_bf16 v[20:23], v[172:175], v[204:207], v[20:23]
	v_mfma_f32_16x16x32_bf16 v[0:3], v[180:183], v[212:215], v[0:3]
	v_mfma_f32_16x16x32_bf16 v[36:39], v[172:175], v[196:199], v[36:39]
	v_mfma_f32_16x16x32_bf16 v[48:51], v[180:183], v[188:191], v[48:51]
	v_mfma_f32_16x16x32_bf16 v[4:7], v[172:175], v[212:215], v[4:7]
	v_mfma_f32_16x16x32_bf16 v[16:19], v[180:183], v[204:207], v[16:19]
	s_setprio 0
	s_barrier
	s_add_i32 s66, 0, 0x18000
	v_add_u32_e32 v155, s66, v149
	s_add_i32 s67, 0, 0x1c000
	ds_read_b128 v[144:147], v155
	ds_read_b128 v[156:159], v155 offset:1024
	ds_read_b128 v[160:163], v155 offset:2048
	ds_read_b128 v[164:167], v155 offset:3072
	v_add_u32_e32 v155, s67, v149
	ds_read_b128 v[168:171], v155
	ds_read_b128 v[172:175], v155 offset:1024
	ds_read_b128 v[176:179], v155 offset:2048
	ds_read_b128 v[180:183], v155 offset:3072
	s_add_u32 s36, s36, 0x40000
	s_addc_u32 s37, s37, 0
	s_mov_b32 m0, s43
	v_lshl_add_u64 v[224:225], s[36:37], 0, v[134:135]
	ds_read_b128 v[184:187], v153 offset:32768
	ds_read_b128 v[188:191], v153 offset:33792
	ds_read_b128 v[192:195], v153 offset:34816
	ds_read_b128 v[196:199], v153 offset:35840
	ds_read_b128 v[200:203], v153 offset:36864
	ds_read_b128 v[204:207], v153 offset:37888
	ds_read_b128 v[208:211], v153 offset:38912
	ds_read_b128 v[212:215], v153 offset:39936
	global_load_lds_dwordx4 v[224:225], off
	v_lshl_add_u64 v[224:225], s[36:37], 0, v[130:131]
	s_mov_b32 m0, s46
	s_nop 0
	global_load_lds_dwordx4 v[224:225], off
	s_waitcnt vmcnt(8)
	s_waitcnt lgkmcnt(0)
	s_barrier
	s_setprio 1
	s_waitcnt lgkmcnt(0)
	v_mfma_f32_16x16x32_bf16 v[124:127], v[144:147], v[184:187], v[124:127]
	v_mfma_f32_16x16x32_bf16 v[104:107], v[160:163], v[192:195], v[104:107]
	v_mfma_f32_16x16x32_bf16 v[92:95], v[144:147], v[200:203], v[92:95]
	v_mfma_f32_16x16x32_bf16 v[72:75], v[160:163], v[208:211], v[72:75]
	v_mfma_f32_16x16x32_bf16 v[108:111], v[144:147], v[192:195], v[108:111]
	v_mfma_f32_16x16x32_bf16 v[120:123], v[160:163], v[184:187], v[120:123]
	v_mfma_f32_16x16x32_bf16 v[76:79], v[144:147], v[208:211], v[76:79]
	v_mfma_f32_16x16x32_bf16 v[88:91], v[160:163], v[200:203], v[88:91]
	v_mfma_f32_16x16x32_bf16 v[124:127], v[156:159], v[188:191], v[124:127]
	v_mfma_f32_16x16x32_bf16 v[104:107], v[164:167], v[196:199], v[104:107]
	v_mfma_f32_16x16x32_bf16 v[92:95], v[156:159], v[204:207], v[92:95]
	v_mfma_f32_16x16x32_bf16 v[72:75], v[164:167], v[212:215], v[72:75]
	v_mfma_f32_16x16x32_bf16 v[108:111], v[156:159], v[196:199], v[108:111]
	v_mfma_f32_16x16x32_bf16 v[120:123], v[164:167], v[188:191], v[120:123]
	v_mfma_f32_16x16x32_bf16 v[76:79], v[156:159], v[212:215], v[76:79]
	v_mfma_f32_16x16x32_bf16 v[88:91], v[164:167], v[204:207], v[88:91]
	s_setprio 0
	s_setprio 1
	v_mfma_f32_16x16x32_bf16 v[116:119], v[168:171], v[184:187], v[116:119]
	v_mfma_f32_16x16x32_bf16 v[96:99], v[176:179], v[192:195], v[96:99]
	v_mfma_f32_16x16x32_bf16 v[84:87], v[168:171], v[200:203], v[84:87]
	v_mfma_f32_16x16x32_bf16 v[64:67], v[176:179], v[208:211], v[64:67]
	v_mfma_f32_16x16x32_bf16 v[100:103], v[168:171], v[192:195], v[100:103]
	v_mfma_f32_16x16x32_bf16 v[112:115], v[176:179], v[184:187], v[112:115]
	v_mfma_f32_16x16x32_bf16 v[68:71], v[168:171], v[208:211], v[68:71]
	v_mfma_f32_16x16x32_bf16 v[80:83], v[176:179], v[200:203], v[80:83]
	v_mfma_f32_16x16x32_bf16 v[116:119], v[172:175], v[188:191], v[116:119]
	v_mfma_f32_16x16x32_bf16 v[96:99], v[180:183], v[196:199], v[96:99]
	v_mfma_f32_16x16x32_bf16 v[84:87], v[172:175], v[204:207], v[84:87]
	v_mfma_f32_16x16x32_bf16 v[64:67], v[180:183], v[212:215], v[64:67]
	v_mfma_f32_16x16x32_bf16 v[100:103], v[172:175], v[196:199], v[100:103]
	v_mfma_f32_16x16x32_bf16 v[112:115], v[180:183], v[188:191], v[112:115]
	v_mfma_f32_16x16x32_bf16 v[68:71], v[172:175], v[212:215], v[68:71]
	v_mfma_f32_16x16x32_bf16 v[80:83], v[180:183], v[204:207], v[80:83]
	s_setprio 0
	s_barrier
; #define PG8_STAGE(bufoff, gbase, voff) do { _Pragma("unroll") for (int _i = 0; _i < 2; ++_i) \
;         __builtin_amdgcn_global_load_lds((const unsigned*)((const char*)(gbase) + (voff)[_i]), (PG8_LAS unsigned*)(lds + (bufoff) + ldsw + _i * 8192), 16, 0, 0); } while (0)
; #define PG8_LDA(dst, b, h) do { _Pragma("unroll") for (int m = 0; m < 4; ++m) _Pragma("unroll") for (int k = 0; k < 2; ++k) dst[m][k] = *(const PG8_LAS bf16x8*)(lds + PG8_SA(b, h) + aoff + m * 2048 + k * 1024); } while (0)
; #define PG8_MMA(ai, bj, At, Bt) do { __builtin_amdgcn_s_setprio(1); _Pragma("unroll") for (int m = 0; m < 4; ++m) _Pragma("unroll") for (int n = 0; n < 2; ++n) _Pragma("unroll") for (int k = 0; k < 2; ++k) \
;         acc[ai][bj][m][n] = __builtin_amdgcn_mfma_f32_16x16x32_bf16(Bt[n][k], At[m][k], acc[ai][bj][m][n], 0, 0, 0); __builtin_amdgcn_s_setprio(0); } while (0)
; #define PG8_WAIT_V(n) asm volatile("s_waitcnt vmcnt(" #n ")" ::: "memory")
; #define PG8_WAIT_L(n) asm volatile("s_waitcnt lgkmcnt(" #n ")" ::: "memory")
; #define PG8_BAR __builtin_amdgcn_s_barrier()
; #define PG8_SCHED __builtin_amdgcn_sched_barrier(0)
; template <class Epi, class Sched, bool ALIGN_EPI = false, bool SP2 = false>
; __device__ __forceinline__ void gemm_phase(PG8_LAS unsigned char* lds, const Gemm g, const Sched& S, const Epi& E) {
;     ...
;             PG8_LDA(At, 1, 1); PG8_STAGE(PG8_SB(1, 0), b3, voffB); PG8_STAGE(PG8_SB(1, 1), b3 + hstep, voffB); PG8_STAGE(PG8_SA(1, 0), a3, voffA);
;             PG8_WAIT_V(8); PG8_WAIT_L(0); PG8_BAR; PG8_MMA(1, 0, At, B0); PG8_MMA(1, 1, At, B1); PG8_BAR; PG8_SCHED;
;     __device__ __forceinline__ void operator()(const f32x4 (&acc)[2][2][4][2], const Unit& u, int wr, int wc, int fr, int fq) const {
;     ...
;             for (int m = 0; m < 4; ++m) { const int row = rbase + ai * 128 + m * 16; const f32x4* sp = (const f32x4*)(SSP + (size_t)row * 16);
;                 const f32x4 s4 = (sp[0] + sp[1]) + (sp[2] + sp[3]); const float rstd = __builtin_amdgcn_rsqf(((s4[0] + s4[1]) + (s4[2] + s4[3])) * (1.0f / 1024.0f) + EPS);
	s_add_i32 s36, s66, s39
	v_lshl_add_u64 v[216:217], v[216:217], 0, s[14:15]
	s_mov_b32 m0, s36
	ds_read_b128 v[184:187], v153 offset:49152
	ds_read_b128 v[188:191], v153 offset:50176
	ds_read_b128 v[192:195], v153 offset:51200
	ds_read_b128 v[196:199], v153 offset:52224
	ds_read_b128 v[200:203], v153 offset:53248
	ds_read_b128 v[204:207], v153 offset:54272
	ds_read_b128 v[208:211], v153 offset:55296
	ds_read_b128 v[212:215], v153 offset:56320
	global_load_lds_dwordx4 v[216:217], off
	s_add_i32 m0, s36, 0x2000
	s_add_u32 s34, s34, 0x40080
	v_lshl_add_u64 v[216:217], v[218:219], 0, s[14:15]
	s_addc_u32 s35, s35, 0
	s_add_i32 s36, s67, s39
	global_load_lds_dwordx4 v[216:217], off
	v_lshl_add_u64 v[216:217], s[34:35], 0, v[132:133]
	s_mov_b32 m0, s36
	s_nop 0
	global_load_lds_dwordx4 v[216:217], off
	v_lshl_add_u64 v[216:217], s[34:35], 0, v[128:129]
	s_add_i32 m0, s36, 0x2000
	s_nop 0
	global_load_lds_dwordx4 v[216:217], off
	v_lshl_add_u64 v[216:217], v[220:221], 0, s[14:15]
	s_mov_b32 m0, s49
	s_nop 0
	global_load_lds_dwordx4 v[216:217], off
	v_lshl_add_u64 v[216:217], v[222:223], 0, s[14:15]
	s_mov_b32 m0, s50
	s_nop 0
	global_load_lds_dwordx4 v[216:217], off
	s_waitcnt vmcnt(8)
	s_waitcnt lgkmcnt(0)
	s_barrier
	s_setprio 1
	s_waitcnt lgkmcnt(0)
	v_mfma_f32_16x16x32_bf16 v[60:63], v[144:147], v[184:187], v[60:63]
	v_mfma_f32_16x16x32_bf16 v[40:43], v[160:163], v[192:195], v[40:43]
	v_mfma_f32_16x16x32_bf16 v[28:31], v[144:147], v[200:203], v[28:31]
	v_mfma_f32_16x16x32_bf16 v[8:11], v[160:163], v[208:211], v[8:11]
	v_mfma_f32_16x16x32_bf16 v[44:47], v[144:147], v[192:195], v[44:47]
	v_mfma_f32_16x16x32_bf16 v[56:59], v[160:163], v[184:187], v[56:59]
	v_mfma_f32_16x16x32_bf16 v[12:15], v[144:147], v[208:211], v[12:15]
	v_mfma_f32_16x16x32_bf16 v[24:27], v[160:163], v[200:203], v[24:27]
	v_mfma_f32_16x16x32_bf16 v[60:63], v[156:159], v[188:191], v[60:63]
	v_mfma_f32_16x16x32_bf16 v[40:43], v[164:167], v[196:199], v[40:43]
	v_mfma_f32_16x16x32_bf16 v[28:31], v[156:159], v[204:207], v[28:31]
	v_mfma_f32_16x16x32_bf16 v[8:11], v[164:167], v[212:215], v[8:11]
	v_mfma_f32_16x16x32_bf16 v[44:47], v[156:159], v[196:199], v[44:47]
	v_mfma_f32_16x16x32_bf16 v[56:59], v[164:167], v[188:191], v[56:59]
	v_mfma_f32_16x16x32_bf16 v[12:15], v[156:159], v[212:215], v[12:15]
	v_mfma_f32_16x16x32_bf16 v[24:27], v[164:167], v[204:207], v[24:27]
	s_setprio 0
	s_setprio 1
	v_mfma_f32_16x16x32_bf16 v[52:55], v[168:171], v[184:187], v[52:55]
	v_mfma_f32_16x16x32_bf16 v[32:35], v[176:179], v[192:195], v[32:35]
	v_mfma_f32_16x16x32_bf16 v[20:23], v[168:171], v[200:203], v[20:23]
	v_mfma_f32_16x16x32_bf16 v[0:3], v[176:179], v[208:211], v[0:3]
	v_mfma_f32_16x16x32_bf16 v[36:39], v[168:171], v[192:195], v[36:39]
	v_mfma_f32_16x16x32_bf16 v[48:51], v[176:179], v[184:187], v[48:51]
	v_mfma_f32_16x16x32_bf16 v[4:7], v[168:171], v[208:211], v[4:7]
	v_mfma_f32_16x16x32_bf16 v[16:19], v[176:179], v[200:203], v[16:19]
	v_mfma_f32_16x16x32_bf16 v[52:55], v[172:175], v[188:191], v[52:55]
	v_mfma_f32_16x16x32_bf16 v[32:35], v[180:183], v[196:199], v[32:35]
	v_mfma_f32_16x16x32_bf16 v[20:23], v[172:175], v[204:207], v[20:23]
	v_mfma_f32_16x16x32_bf16 v[0:3], v[180:183], v[212:215], v[0:3]
	v_mfma_f32_16x16x32_bf16 v[36:39], v[172:175], v[196:199], v[36:39]
	v_mfma_f32_16x16x32_bf16 v[48:51], v[180:183], v[188:191], v[48:51]
	v_mfma_f32_16x16x32_bf16 v[4:7], v[172:175], v[212:215], v[4:7]
	v_mfma_f32_16x16x32_bf16 v[16:19], v[180:183], v[204:207], v[16:19]
	s_setprio 0
	s_barrier
	s_mov_b32 s99, 0
	s_add_i32 s65, s65, 2
	s_add_u32 s30, s30, 0x100
	s_addc_u32 s31, s31, 0
	s_add_u32 s63, s63, 0x100
	s_addc_u32 s64, s64, 0
	s_cmp_gt_u32 s65, 13
	s_cbranch_scc0 .LBB0_1540
	v_lshl_add_u32 v146, s28, 8, v148
	v_ashrrev_i32_e32 v147, 31, v146
	v_lshlrev_b64 v[144:145], 6, v[146:147]
	v_lshl_add_u64 v[144:145], s[12:13], 0, v[144:145]
	global_load_dwordx4 v[156:159], v[144:145], off
	global_load_dwordx4 v[160:163], v[144:145], off offset:16
	global_load_dwordx4 v[164:167], v[144:145], off offset:32
	global_load_dwordx4 v[168:171], v[144:145], off offset:48
	global_load_dwordx4 v[172:175], v[144:145], off offset:1024
	global_load_dwordx4 v[176:179], v[144:145], off offset:1040
	global_load_dwordx4 v[180:183], v[144:145], off offset:1056
	global_load_dwordx4 v[184:187], v[144:145], off offset:1072
	global_load_dwordx4 v[188:191], v[144:145], off offset:2048
	global_load_dwordx4 v[192:195], v[144:145], off offset:2064
	global_load_dwordx4 v[196:199], v[144:145], off offset:2080
	global_load_dwordx4 v[200:203], v[144:145], off offset:2096
	global_load_dwordx4 v[204:207], v[144:145], off offset:3072
	global_load_dwordx4 v[208:211], v[144:145], off offset:3088
	global_load_dwordx4 v[212:215], v[144:145], off offset:3104
	global_load_dwordx4 v[216:219], v[144:145], off offset:3120
	s_and_b64 vcc, exec, s[16:17]
	s_cbranch_vccz .LBB0_1543
	s_barrier

; #define PG8_STAGE(bufoff, gbase, voff) do { _Pragma("unroll") for (int _i = 0; _i < 2; ++_i) \
;         __builtin_amdgcn_global_load_lds((const unsigned*)((const char*)(gbase) + (voff)[_i]), (PG8_LAS unsigned*)(lds + (bufoff) + ldsw + _i * 8192), 16, 0, 0); } while (0)
; #define PG8_LDA(dst, b, h) do { _Pragma("unroll") for (int m = 0; m < 4; ++m) _Pragma("unroll") for (int k = 0; k < 2; ++k) dst[m][k] = *(const PG8_LAS bf16x8*)(lds + PG8_SA(b, h) + aoff + m * 2048 + k * 1024); } while (0)
; #define PG8_MMA(ai, bj, At, Bt) do { __builtin_amdgcn_s_setprio(1); _Pragma("unroll") for (int m = 0; m < 4; ++m) _Pragma("unroll") for (int n = 0; n < 2; ++n) _Pragma("unroll") for (int k = 0; k < 2; ++k) \
;         acc[ai][bj][m][n] = __builtin_amdgcn_mfma_f32_16x16x32_bf16(Bt[n][k], At[m][k], acc[ai][bj][m][n], 0, 0, 0); __builtin_amdgcn_s_setprio(0); } while (0)
; #define PG8_WAIT_V(n) asm volatile("s_waitcnt vmcnt(" #n ")" ::: "memory")
; #define PG8_WAIT_L(n) asm volatile("s_waitcnt lgkmcnt(" #n ")" ::: "memory")
; #define PG8_BAR __builtin_amdgcn_s_barrier()
; #define PG8_SCHED __builtin_amdgcn_sched_barrier(0)
; template <class Epi, class Sched, bool ALIGN_EPI = false, bool SP2 = false>
; __device__ __forceinline__ void gemm_phase(PG8_LAS unsigned char* lds, const Gemm g, const Sched& S, const Epi& E) {
;     ...
;             PG8_WAIT_V(8); PG8_WAIT_L(0); PG8_BAR; PG8_MMA(0, 0, At, B0); PG8_MMA(0, 1, At, B1); PG8_BAR; PG8_SCHED;
;             PG8_LDA(At, 0, 1); PG8_STAGE(PG8_SB(0, 0), b2, voffB); PG8_STAGE(PG8_SB(0, 1), b2 + hstep, voffB); PG8_STAGE(PG8_SA(0, 0), a2, voffA);
.Lrj_P6_0:
	s_waitcnt lgkmcnt(0)
	s_barrier
	s_setprio 1
	s_waitcnt lgkmcnt(0)
	v_mfma_f32_16x16x32_bf16 v[124:127], v[152:155], v[184:187], v[124:127]
	v_mfma_f32_16x16x32_bf16 v[104:107], v[160:163], v[192:195], v[104:107]
	v_mfma_f32_16x16x32_bf16 v[92:95], v[152:155], v[200:203], v[92:95]
	v_mfma_f32_16x16x32_bf16 v[72:75], v[160:163], v[208:211], v[72:75]
	v_mfma_f32_16x16x32_bf16 v[108:111], v[152:155], v[192:195], v[108:111]
	v_mfma_f32_16x16x32_bf16 v[120:123], v[160:163], v[184:187], v[120:123]
	v_mfma_f32_16x16x32_bf16 v[76:79], v[152:155], v[208:211], v[76:79]
	v_mfma_f32_16x16x32_bf16 v[88:91], v[160:163], v[200:203], v[88:91]
	v_mfma_f32_16x16x32_bf16 v[124:127], v[156:159], v[188:191], v[124:127]
	v_mfma_f32_16x16x32_bf16 v[104:107], v[164:167], v[196:199], v[104:107]
	v_mfma_f32_16x16x32_bf16 v[92:95], v[156:159], v[204:207], v[92:95]
	v_mfma_f32_16x16x32_bf16 v[72:75], v[164:167], v[212:215], v[72:75]
	v_mfma_f32_16x16x32_bf16 v[108:111], v[156:159], v[196:199], v[108:111]
	v_mfma_f32_16x16x32_bf16 v[120:123], v[164:167], v[188:191], v[120:123]
	v_mfma_f32_16x16x32_bf16 v[76:79], v[156:159], v[212:215], v[76:79]
	v_mfma_f32_16x16x32_bf16 v[88:91], v[164:167], v[204:207], v[88:91]
	s_setprio 0
	s_setprio 1
	v_mfma_f32_16x16x32_bf16 v[116:119], v[168:171], v[184:187], v[116:119]
	v_mfma_f32_16x16x32_bf16 v[96:99], v[176:179], v[192:195], v[96:99]
	v_mfma_f32_16x16x32_bf16 v[84:87], v[168:171], v[200:203], v[84:87]
	v_mfma_f32_16x16x32_bf16 v[64:67], v[176:179], v[208:211], v[64:67]
	v_mfma_f32_16x16x32_bf16 v[100:103], v[168:171], v[192:195], v[100:103]
	v_mfma_f32_16x16x32_bf16 v[112:115], v[176:179], v[184:187], v[112:115]
	v_mfma_f32_16x16x32_bf16 v[68:71], v[168:171], v[208:211], v[68:71]
	v_mfma_f32_16x16x32_bf16 v[80:83], v[176:179], v[200:203], v[80:83]
	v_mfma_f32_16x16x32_bf16 v[116:119], v[172:175], v[188:191], v[116:119]
	v_mfma_f32_16x16x32_bf16 v[96:99], v[180:183], v[196:199], v[96:99]
	v_mfma_f32_16x16x32_bf16 v[84:87], v[172:175], v[204:207], v[84:87]
	v_mfma_f32_16x16x32_bf16 v[64:67], v[180:183], v[212:215], v[64:67]
	v_mfma_f32_16x16x32_bf16 v[100:103], v[172:175], v[196:199], v[100:103]
	v_mfma_f32_16x16x32_bf16 v[112:115], v[180:183], v[188:191], v[112:115]
	v_mfma_f32_16x16x32_bf16 v[68:71], v[172:175], v[212:215], v[68:71]
	v_mfma_f32_16x16x32_bf16 v[80:83], v[180:183], v[204:207], v[80:83]
	s_setprio 0
	s_barrier
	s_add_i32 s69, s51, s39
	v_lshl_add_u64 v[144:145], s[30:31], 0, v[132:133]
	s_mov_b32 m0, s69
	ds_read_b128 v[184:187], v151 offset:16384
	ds_read_b128 v[188:191], v151 offset:17408
	ds_read_b128 v[192:195], v151 offset:18432
	ds_read_b128 v[196:199], v151 offset:19456
	ds_read_b128 v[200:203], v151 offset:20480
	ds_read_b128 v[204:207], v151 offset:21504
	ds_read_b128 v[208:211], v151 offset:22528
	ds_read_b128 v[212:215], v151 offset:23552
	global_load_lds_dwordx4 v[144:145], off
	s_add_i32 m0, s69, 0x2000
	s_add_u32 s70, s30, 0x100000
	v_lshl_add_u64 v[216:217], s[30:31], 0, v[128:129]
	s_addc_u32 s71, s31, 0
	s_add_i32 s69, s52, s39
	global_load_lds_dwordx4 v[216:217], off
	v_lshl_add_u64 v[218:219], s[70:71], 0, v[132:133]
	s_mov_b32 m0, s69
	v_lshl_add_u64 v[220:221], s[34:35], 0, v[130:131]
	global_load_lds_dwordx4 v[218:219], off
	v_lshl_add_u64 v[218:219], s[70:71], 0, v[128:129]
	s_add_i32 m0, s69, 0x2000
	s_nop 0
	global_load_lds_dwordx4 v[218:219], off
	v_lshl_add_u64 v[218:219], s[34:35], 0, v[134:135]
	s_mov_b32 m0, s27
	s_nop 0
	global_load_lds_dwordx4 v[218:219], off
	s_mov_b32 m0, s42
	s_nop 0
	global_load_lds_dwordx4 v[220:221], off
	s_cmp_eq_u32 s99, 1
	s_cbranch_scc1 .Lrw_P6_1
	s_waitcnt vmcnt(8)
	s_branch .Lrj_P6_1

; #define PG8_STAGE(bufoff, gbase, voff) do { _Pragma("unroll") for (int _i = 0; _i < 2; ++_i) \
;         __builtin_amdgcn_global_load_lds((const unsigned*)((const char*)(gbase) + (voff)[_i]), (PG8_LAS unsigned*)(lds + (bufoff) + ldsw + _i * 8192), 16, 0, 0); } while (0)
; #define PG8_LDA(dst, b, h) do { _Pragma("unroll") for (int m = 0; m < 4; ++m) _Pragma("unroll") for (int k = 0; k < 2; ++k) dst[m][k] = *(const PG8_LAS bf16x8*)(lds + PG8_SA(b, h) + aoff + m * 2048 + k * 1024); } while (0)
; #define PG8_LDB(dst, b, h) do { _Pragma("unroll") for (int n = 0; n < 2; ++n) _Pragma("unroll") for (int k = 0; k < 2; ++k) dst[n][k] = *(const PG8_LAS bf16x8*)(lds + PG8_SB(b, h) + boff + n * 2048 + k * 1024); } while (0)
; #define PG8_MMA(ai, bj, At, Bt) do { __builtin_amdgcn_s_setprio(1); _Pragma("unroll") for (int m = 0; m < 4; ++m) _Pragma("unroll") for (int n = 0; n < 2; ++n) _Pragma("unroll") for (int k = 0; k < 2; ++k) \
;         acc[ai][bj][m][n] = __builtin_amdgcn_mfma_f32_16x16x32_bf16(Bt[n][k], At[m][k], acc[ai][bj][m][n], 0, 0, 0); __builtin_amdgcn_s_setprio(0); } while (0)
; #define PG8_WAIT_V(n) asm volatile("s_waitcnt vmcnt(" #n ")" ::: "memory")
; #define PG8_WAIT_L(n) asm volatile("s_waitcnt lgkmcnt(" #n ")" ::: "memory")
; #define PG8_BAR __builtin_amdgcn_s_barrier()
; #define PG8_SCHED __builtin_amdgcn_sched_barrier(0)
; template <class Epi, class Sched, bool ALIGN_EPI = false, bool SP2 = false>
; __device__ __forceinline__ void gemm_phase(PG8_LAS unsigned char* lds, const Gemm g, const Sched& S, const Epi& E) {
;     ...
;             PG8_WAIT_V(8); PG8_WAIT_L(0); PG8_BAR; PG8_MMA(1, 0, At, B0); PG8_MMA(1, 1, At, B1); PG8_BAR; PG8_SCHED;
;             PG8_LDB(B0, 1, 0); PG8_LDB(B1, 1, 1); PG8_SCHED; PG8_LDA(At, 1, 0); PG8_STAGE(PG8_SA(0, 1), a2 + hstep, voffA);
;             PG8_WAIT_V(8); PG8_WAIT_L(0); PG8_BAR; PG8_MMA(0, 0, At, B0); PG8_MMA(0, 1, At, B1); PG8_BAR; PG8_SCHED;
.Lrj_P6_1:
	s_waitcnt lgkmcnt(0)
	s_barrier
	s_setprio 1
	s_waitcnt lgkmcnt(0)
	v_mfma_f32_16x16x32_bf16 v[60:63], v[152:155], v[184:187], v[60:63]
	v_mfma_f32_16x16x32_bf16 v[40:43], v[160:163], v[192:195], v[40:43]
	v_mfma_f32_16x16x32_bf16 v[28:31], v[152:155], v[200:203], v[28:31]
	v_mfma_f32_16x16x32_bf16 v[8:11], v[160:163], v[208:211], v[8:11]
	v_mfma_f32_16x16x32_bf16 v[44:47], v[152:155], v[192:195], v[44:47]
	v_mfma_f32_16x16x32_bf16 v[56:59], v[160:163], v[184:187], v[56:59]
	v_mfma_f32_16x16x32_bf16 v[12:15], v[152:155], v[208:211], v[12:15]
	v_mfma_f32_16x16x32_bf16 v[24:27], v[160:163], v[200:203], v[24:27]
	v_mfma_f32_16x16x32_bf16 v[60:63], v[156:159], v[188:191], v[60:63]
	v_mfma_f32_16x16x32_bf16 v[40:43], v[164:167], v[196:199], v[40:43]
	v_mfma_f32_16x16x32_bf16 v[28:31], v[156:159], v[204:207], v[28:31]
	v_mfma_f32_16x16x32_bf16 v[8:11], v[164:167], v[212:215], v[8:11]
	v_mfma_f32_16x16x32_bf16 v[44:47], v[156:159], v[196:199], v[44:47]
	v_mfma_f32_16x16x32_bf16 v[56:59], v[164:167], v[188:191], v[56:59]
	v_mfma_f32_16x16x32_bf16 v[12:15], v[156:159], v[212:215], v[12:15]
	v_mfma_f32_16x16x32_bf16 v[24:27], v[164:167], v[204:207], v[24:27]
	s_setprio 0
	s_setprio 1
	v_mfma_f32_16x16x32_bf16 v[52:55], v[168:171], v[184:187], v[52:55]
	v_mfma_f32_16x16x32_bf16 v[32:35], v[176:179], v[192:195], v[32:35]
	v_mfma_f32_16x16x32_bf16 v[20:23], v[168:171], v[200:203], v[20:23]
	v_mfma_f32_16x16x32_bf16 v[0:3], v[176:179], v[208:211], v[0:3]
	v_mfma_f32_16x16x32_bf16 v[36:39], v[168:171], v[192:195], v[36:39]
	v_mfma_f32_16x16x32_bf16 v[48:51], v[176:179], v[184:187], v[48:51]
	v_mfma_f32_16x16x32_bf16 v[4:7], v[168:171], v[208:211], v[4:7]
	v_mfma_f32_16x16x32_bf16 v[16:19], v[176:179], v[200:203], v[16:19]
	v_mfma_f32_16x16x32_bf16 v[52:55], v[172:175], v[188:191], v[52:55]
	v_mfma_f32_16x16x32_bf16 v[32:35], v[180:183], v[196:199], v[32:35]
	v_mfma_f32_16x16x32_bf16 v[20:23], v[172:175], v[204:207], v[20:23]
	v_mfma_f32_16x16x32_bf16 v[0:3], v[180:183], v[212:215], v[0:3]
	v_mfma_f32_16x16x32_bf16 v[36:39], v[172:175], v[196:199], v[36:39]
	v_mfma_f32_16x16x32_bf16 v[48:51], v[180:183], v[188:191], v[48:51]
	v_mfma_f32_16x16x32_bf16 v[4:7], v[172:175], v[212:215], v[4:7]
	v_mfma_f32_16x16x32_bf16 v[16:19], v[180:183], v[204:207], v[16:19]
	s_setprio 0
	s_barrier
	s_add_i32 s69, 0, 0x18000
	s_add_i32 s70, 0, 0x1c000
	v_add_u32_e32 v164, s69, v147
	v_add_u32_e32 v180, s70, v147
	ds_read_b128 v[152:155], v164
	ds_read_b128 v[156:159], v164 offset:1024
	ds_read_b128 v[160:163], v164 offset:2048
	ds_read_b128 v[164:167], v164 offset:3072
	ds_read_b128 v[168:171], v180
	ds_read_b128 v[172:175], v180 offset:1024
	ds_read_b128 v[176:179], v180 offset:2048
	ds_read_b128 v[180:183], v180 offset:3072
	s_add_u32 s34, s34, 0x100000
	s_addc_u32 s35, s35, 0
	s_mov_b32 m0, s43
	v_lshl_add_u64 v[222:223], s[34:35], 0, v[134:135]
	ds_read_b128 v[184:187], v151 offset:32768
	ds_read_b128 v[188:191], v151 offset:33792
	ds_read_b128 v[192:195], v151 offset:34816
	ds_read_b128 v[196:199], v151 offset:35840
	ds_read_b128 v[200:203], v151 offset:36864
	ds_read_b128 v[204:207], v151 offset:37888
	ds_read_b128 v[208:211], v151 offset:38912
	ds_read_b128 v[212:215], v151 offset:39936
	global_load_lds_dwordx4 v[222:223], off
	v_lshl_add_u64 v[222:223], s[34:35], 0, v[130:131]
	s_mov_b32 m0, s46
	s_nop 0
	global_load_lds_dwordx4 v[222:223], off
	s_waitcnt vmcnt(8)
	s_waitcnt lgkmcnt(0)
	s_barrier
	s_setprio 1
	s_waitcnt lgkmcnt(0)
	v_mfma_f32_16x16x32_bf16 v[124:127], v[152:155], v[184:187], v[124:127]
	v_mfma_f32_16x16x32_bf16 v[104:107], v[160:163], v[192:195], v[104:107]
	v_mfma_f32_16x16x32_bf16 v[92:95], v[152:155], v[200:203], v[92:95]
	v_mfma_f32_16x16x32_bf16 v[72:75], v[160:163], v[208:211], v[72:75]
	v_mfma_f32_16x16x32_bf16 v[108:111], v[152:155], v[192:195], v[108:111]
	v_mfma_f32_16x16x32_bf16 v[120:123], v[160:163], v[184:187], v[120:123]
	v_mfma_f32_16x16x32_bf16 v[76:79], v[152:155], v[208:211], v[76:79]
	v_mfma_f32_16x16x32_bf16 v[88:91], v[160:163], v[200:203], v[88:91]
	v_mfma_f32_16x16x32_bf16 v[124:127], v[156:159], v[188:191], v[124:127]
	v_mfma_f32_16x16x32_bf16 v[104:107], v[164:167], v[196:199], v[104:107]
	v_mfma_f32_16x16x32_bf16 v[92:95], v[156:159], v[204:207], v[92:95]
	v_mfma_f32_16x16x32_bf16 v[72:75], v[164:167], v[212:215], v[72:75]
	v_mfma_f32_16x16x32_bf16 v[108:111], v[156:159], v[196:199], v[108:111]
	v_mfma_f32_16x16x32_bf16 v[120:123], v[164:167], v[188:191], v[120:123]
	v_mfma_f32_16x16x32_bf16 v[76:79], v[156:159], v[212:215], v[76:79]
	v_mfma_f32_16x16x32_bf16 v[88:91], v[164:167], v[204:207], v[88:91]
	s_setprio 0
	s_setprio 1
	v_mfma_f32_16x16x32_bf16 v[116:119], v[168:171], v[184:187], v[116:119]
	v_mfma_f32_16x16x32_bf16 v[96:99], v[176:179], v[192:195], v[96:99]
	v_mfma_f32_16x16x32_bf16 v[84:87], v[168:171], v[200:203], v[84:87]
	v_mfma_f32_16x16x32_bf16 v[64:67], v[176:179], v[208:211], v[64:67]
	v_mfma_f32_16x16x32_bf16 v[100:103], v[168:171], v[192:195], v[100:103]
	v_mfma_f32_16x16x32_bf16 v[112:115], v[176:179], v[184:187], v[112:115]
	v_mfma_f32_16x16x32_bf16 v[68:71], v[168:171], v[208:211], v[68:71]
	v_mfma_f32_16x16x32_bf16 v[80:83], v[176:179], v[200:203], v[80:83]
	v_mfma_f32_16x16x32_bf16 v[116:119], v[172:175], v[188:191], v[116:119]
	v_mfma_f32_16x16x32_bf16 v[96:99], v[180:183], v[196:199], v[96:99]
	v_mfma_f32_16x16x32_bf16 v[84:87], v[172:175], v[204:207], v[84:87]
	v_mfma_f32_16x16x32_bf16 v[64:67], v[180:183], v[212:215], v[64:67]
	v_mfma_f32_16x16x32_bf16 v[100:103], v[172:175], v[196:199], v[100:103]
	v_mfma_f32_16x16x32_bf16 v[112:115], v[180:183], v[188:191], v[112:115]
	v_mfma_f32_16x16x32_bf16 v[68:71], v[172:175], v[212:215], v[68:71]
	v_mfma_f32_16x16x32_bf16 v[80:83], v[180:183], v[204:207], v[80:83]
	s_setprio 0
	s_barrier
; #define PG8_STAGE(bufoff, gbase, voff) do { _Pragma("unroll") for (int _i = 0; _i < 2; ++_i) \
;         __builtin_amdgcn_global_load_lds((const unsigned*)((const char*)(gbase) + (voff)[_i]), (PG8_LAS unsigned*)(lds + (bufoff) + ldsw + _i * 8192), 16, 0, 0); } while (0)
; #define PG8_LDA(dst, b, h) do { _Pragma("unroll") for (int m = 0; m < 4; ++m) _Pragma("unroll") for (int k = 0; k < 2; ++k) dst[m][k] = *(const PG8_LAS bf16x8*)(lds + PG8_SA(b, h) + aoff + m * 2048 + k * 1024); } while (0)
; #define PG8_MMA(ai, bj, At, Bt) do { __builtin_amdgcn_s_setprio(1); _Pragma("unroll") for (int m = 0; m < 4; ++m) _Pragma("unroll") for (int n = 0; n < 2; ++n) _Pragma("unroll") for (int k = 0; k < 2; ++k) \
;         acc[ai][bj][m][n] = __builtin_amdgcn_mfma_f32_16x16x32_bf16(Bt[n][k], At[m][k], acc[ai][bj][m][n], 0, 0, 0); __builtin_amdgcn_s_setprio(0); } while (0)
; #define PG8_WAIT_V(n) asm volatile("s_waitcnt vmcnt(" #n ")" ::: "memory")
; #define PG8_WAIT_L(n) asm volatile("s_waitcnt lgkmcnt(" #n ")" ::: "memory")
; #define PG8_BAR __builtin_amdgcn_s_barrier()
; #define PG8_SCHED __builtin_amdgcn_sched_barrier(0)
; template <class Epi, class Sched, bool ALIGN_EPI = false, bool SP2 = false>
; __device__ __forceinline__ void gemm_phase(PG8_LAS unsigned char* lds, const Gemm g, const Sched& S, const Epi& E) {
;     ...
;             PG8_LDA(At, 1, 1); PG8_STAGE(PG8_SB(1, 0), b3, voffB); PG8_STAGE(PG8_SB(1, 1), b3 + hstep, voffB); PG8_STAGE(PG8_SA(1, 0), a3, voffA);
;             PG8_WAIT_V(8); PG8_WAIT_L(0); PG8_BAR; PG8_MMA(1, 0, At, B0); PG8_MMA(1, 1, At, B1); PG8_BAR; PG8_SCHED;
;     __device__ __forceinline__ void operator()(const f32x4 (&acc)[2][2][4][2], const Unit& u, int wr, int wc, int fr, int fq) const {
;     ...
;             for (int m = 0; m < 4; ++m) { float* yr = y + (size_t)(rbase + ai * 128 + m * 16) * 1024 + cb;
; #pragma unroll
;                 for (int bj = 0; bj < 2; ++bj) { float* yp = yr + bj * 128; const f32x4 a = *(const f32x4*)yp + acc[ai][bj][m][0], b = *(const f32x4*)(yp + 4) + acc[ai][bj][m][1]; *(f32x4*)yp = a; *(f32x4*)(yp + 4) = b; }
	s_add_i32 s34, s69, s39
	v_lshl_add_u64 v[144:145], v[144:145], 0, s[6:7]
	s_mov_b32 m0, s34
	ds_read_b128 v[184:187], v151 offset:49152
	ds_read_b128 v[188:191], v151 offset:50176
	ds_read_b128 v[192:195], v151 offset:51200
	ds_read_b128 v[196:199], v151 offset:52224
	ds_read_b128 v[200:203], v151 offset:53248
	ds_read_b128 v[204:207], v151 offset:54272
	ds_read_b128 v[208:211], v151 offset:55296
	ds_read_b128 v[212:215], v151 offset:56320
	global_load_lds_dwordx4 v[144:145], off
	s_add_i32 m0, s34, 0x2000
	s_add_u32 s30, s30, 0x100080
	v_lshl_add_u64 v[144:145], v[216:217], 0, s[6:7]
	s_addc_u32 s31, s31, 0
	s_add_i32 s34, s70, s39
	global_load_lds_dwordx4 v[144:145], off
	v_lshl_add_u64 v[144:145], s[30:31], 0, v[132:133]
	s_mov_b32 m0, s34
	s_nop 0
	global_load_lds_dwordx4 v[144:145], off
	v_lshl_add_u64 v[144:145], s[30:31], 0, v[128:129]
	s_add_i32 m0, s34, 0x2000
	s_nop 0
	global_load_lds_dwordx4 v[144:145], off
	v_lshl_add_u64 v[144:145], v[218:219], 0, s[6:7]
	s_mov_b32 m0, s48
	s_nop 0
	global_load_lds_dwordx4 v[144:145], off
	v_lshl_add_u64 v[144:145], v[220:221], 0, s[6:7]
	s_mov_b32 m0, s49
	s_nop 0
	global_load_lds_dwordx4 v[144:145], off
	s_waitcnt vmcnt(8)
	s_waitcnt lgkmcnt(0)
	s_barrier
	s_setprio 1
	s_waitcnt lgkmcnt(0)
	v_mfma_f32_16x16x32_bf16 v[60:63], v[152:155], v[184:187], v[60:63]
	v_mfma_f32_16x16x32_bf16 v[40:43], v[160:163], v[192:195], v[40:43]
	v_mfma_f32_16x16x32_bf16 v[28:31], v[152:155], v[200:203], v[28:31]
	v_mfma_f32_16x16x32_bf16 v[8:11], v[160:163], v[208:211], v[8:11]
	v_mfma_f32_16x16x32_bf16 v[44:47], v[152:155], v[192:195], v[44:47]
	v_mfma_f32_16x16x32_bf16 v[56:59], v[160:163], v[184:187], v[56:59]
	v_mfma_f32_16x16x32_bf16 v[12:15], v[152:155], v[208:211], v[12:15]
	v_mfma_f32_16x16x32_bf16 v[24:27], v[160:163], v[200:203], v[24:27]
	v_mfma_f32_16x16x32_bf16 v[60:63], v[156:159], v[188:191], v[60:63]
	v_mfma_f32_16x16x32_bf16 v[40:43], v[164:167], v[196:199], v[40:43]
	v_mfma_f32_16x16x32_bf16 v[28:31], v[156:159], v[204:207], v[28:31]
	v_mfma_f32_16x16x32_bf16 v[8:11], v[164:167], v[212:215], v[8:11]
	v_mfma_f32_16x16x32_bf16 v[44:47], v[156:159], v[196:199], v[44:47]
	v_mfma_f32_16x16x32_bf16 v[56:59], v[164:167], v[188:191], v[56:59]
	v_mfma_f32_16x16x32_bf16 v[12:15], v[156:159], v[212:215], v[12:15]
	v_mfma_f32_16x16x32_bf16 v[24:27], v[164:167], v[204:207], v[24:27]
	s_setprio 0
	s_setprio 1
	v_mfma_f32_16x16x32_bf16 v[52:55], v[168:171], v[184:187], v[52:55]
	v_mfma_f32_16x16x32_bf16 v[32:35], v[176:179], v[192:195], v[32:35]
	v_mfma_f32_16x16x32_bf16 v[20:23], v[168:171], v[200:203], v[20:23]
	v_mfma_f32_16x16x32_bf16 v[0:3], v[176:179], v[208:211], v[0:3]
	v_mfma_f32_16x16x32_bf16 v[36:39], v[168:171], v[192:195], v[36:39]
	v_mfma_f32_16x16x32_bf16 v[48:51], v[176:179], v[184:187], v[48:51]
	v_mfma_f32_16x16x32_bf16 v[4:7], v[168:171], v[208:211], v[4:7]
	v_mfma_f32_16x16x32_bf16 v[16:19], v[176:179], v[200:203], v[16:19]
	v_mfma_f32_16x16x32_bf16 v[52:55], v[172:175], v[188:191], v[52:55]
	v_mfma_f32_16x16x32_bf16 v[32:35], v[180:183], v[196:199], v[32:35]
	v_mfma_f32_16x16x32_bf16 v[20:23], v[172:175], v[204:207], v[20:23]
	v_mfma_f32_16x16x32_bf16 v[0:3], v[180:183], v[212:215], v[0:3]
	v_mfma_f32_16x16x32_bf16 v[36:39], v[172:175], v[196:199], v[36:39]
	v_mfma_f32_16x16x32_bf16 v[48:51], v[180:183], v[188:191], v[48:51]
	v_mfma_f32_16x16x32_bf16 v[4:7], v[172:175], v[212:215], v[4:7]
	v_mfma_f32_16x16x32_bf16 v[16:19], v[180:183], v[204:207], v[16:19]
	s_setprio 0
	s_barrier
	s_mov_b32 s99, 0
	s_add_i32 s68, s68, 2
	s_add_u32 s28, s28, 0x100
	s_addc_u32 s29, s29, 0
	s_add_u32 s66, s66, 0x100
	s_addc_u32 s67, s67, 0
	s_cmp_gt_u32 s68, 61
	s_cbranch_scc0 .LBB0_2136
	v_and_b32_e32 v216, 0xfffffff7, v146
	v_lshl_add_u32 v216, s26, 8, v216
	v_bfe_u32 v220, v146, 3, 1
	v_lshl_add_u32 v220, v220, 2, v148
	v_lshl_or_b32 v220, s63, 8, v220
	v_ashrrev_i32_e32 v217, 31, v216
	v_ashrrev_i32_e32 v221, 31, v220
	v_lshlrev_b64 v[216:217], 12, v[216:217]
	v_lshlrev_b64 v[220:221], 2, v[220:221]
	v_lshl_add_u64 v[216:217], s[84:85], 0, v[216:217]
	v_lshl_add_u64 v[216:217], v[216:217], 0, v[220:221]
	s_mov_b64 s[98:99], 0x8000
	v_lshl_add_u64 v[218:219], v[216:217], 0, s[98:99]
	v_mov_b64_e32 v[220:221], v[216:217]
	v_mov_b64_e32 v[222:223], v[218:219]
	s_mov_b64 s[98:99], 0x10000
	s_mov_b64 s[100:101], 0x50000
	global_load_dwordx4 v[152:155], v[216:217], off
	global_load_dwordx4 v[156:159], v[218:219], off
	global_load_dwordx4 v[160:163], v[216:217], off offset:512
	global_load_dwordx4 v[164:167], v[218:219], off offset:512
	v_lshl_add_u64 v[216:217], v[216:217], 0, s[98:99]
	v_lshl_add_u64 v[218:219], v[218:219], 0, s[98:99]
	global_load_dwordx4 v[168:171], v[216:217], off
	global_load_dwordx4 v[172:175], v[218:219], off
	global_load_dwordx4 v[176:179], v[216:217], off offset:512
	global_load_dwordx4 v[180:183], v[218:219], off offset:512
	v_lshl_add_u64 v[216:217], v[216:217], 0, s[98:99]
	v_lshl_add_u64 v[218:219], v[218:219], 0, s[98:99]
	global_load_dwordx4 v[184:187], v[216:217], off
	global_load_dwordx4 v[188:191], v[218:219], off
	global_load_dwordx4 v[192:195], v[216:217], off offset:512
	global_load_dwordx4 v[196:199], v[218:219], off offset:512
	v_lshl_add_u64 v[216:217], v[216:217], 0, s[98:99]
	v_lshl_add_u64 v[218:219], v[218:219], 0, s[98:99]
	global_load_dwordx4 v[200:203], v[216:217], off
	global_load_dwordx4 v[204:207], v[218:219], off
	global_load_dwordx4 v[208:211], v[216:217], off offset:512
	global_load_dwordx4 v[212:215], v[218:219], off offset:512
	v_lshl_add_u64 v[216:217], v[216:217], 0, s[100:101]
	v_lshl_add_u64 v[218:219], v[218:219], 0, s[100:101]
	global_load_dwordx4 v[228:231], v[216:217], off
	global_load_dwordx4 v[232:235], v[218:219], off
	global_load_dwordx4 v[236:239], v[216:217], off offset:512
	global_load_dwordx4 v[240:243], v[218:219], off offset:512
	v_lshl_add_u64 v[216:217], v[216:217], 0, s[98:99]
	v_lshl_add_u64 v[218:219], v[218:219], 0, s[98:99]
	s_and_b64 vcc, exec, s[8:9]
	s_cbranch_vccz .LBB0_2139
	s_barrier
